# K-loops: the 16 redundant s_waitcnt lgkmcnt(0) right after the barriers (MFMA segment heads) removed, on top of the no-setprio kernel
# speedup vs baseline: 1.0052x; 1.0052x over previous
; #define PG8_STAGE(bufoff, gbase, voff) do { _Pragma("unroll") for (int _i = 0; _i < 2; ++_i) \
;         __builtin_amdgcn_global_load_lds((const unsigned*)((const char*)(gbase) + (voff)[_i]), (PG8_LAS unsigned*)(lds + (bufoff) + ldsw + _i * 8192), 16, 0, 0); } while (0)
; #define PG8_LDA(dst, b, h) do { _Pragma("unroll") for (int m = 0; m < 4; ++m) _Pragma("unroll") for (int k = 0; k < 2; ++k) dst[m][k] = *(const PG8_LAS bf16x8*)(lds + PG8_SA(b, h) + aoff + m * 2048 + k * 1024); } while (0)
; #define PG8_LDB(dst, b, h) do { _Pragma("unroll") for (int n = 0; n < 2; ++n) _Pragma("unroll") for (int k = 0; k < 2; ++k) dst[n][k] = *(const PG8_LAS bf16x8*)(lds + PG8_SB(b, h) + boff + n * 2048 + k * 1024); } while (0)
; #define PG8_MMA(ai, bj, At, Bt) do { __builtin_amdgcn_s_setprio(1); _Pragma("unroll") for (int m = 0; m < 4; ++m) _Pragma("unroll") for (int n = 0; n < 2; ++n) _Pragma("unroll") for (int k = 0; k < 2; ++k) \
;         acc[ai][bj][m][n] = __builtin_amdgcn_mfma_f32_16x16x32_bf16(Bt[n][k], At[m][k], acc[ai][bj][m][n], 0, 0, 0); __builtin_amdgcn_s_setprio(0); } while (0)
; #define PG8_WAIT_V(n) asm volatile("s_waitcnt vmcnt(" #n ")" ::: "memory")
; #define PG8_WAIT_L(n) asm volatile("s_waitcnt lgkmcnt(" #n ")" ::: "memory")
; template <class Epi, class Sched, bool ALIGN_EPI = false, bool SP2 = false>
; __device__ __forceinline__ void gemm_phase(PG8_LAS unsigned char* lds, const Gemm g, const Sched& S, const Epi& E) {
;     ...
;             const bool last = (t == nt - 2);
;             const char* a1 = cA + (size_t)(t + 1) * kstep;
;             const char* a2 = last ? nA : cA + (size_t)(t + 2) * kstep; const char* b2 = last ? nB : cB + (size_t)(t + 2) * kstep;
;             const char* a3 = a2 + kstep; const char* b3 = b2 + kstep;
;             if (last && has_next) S.a_ready(nxt);
;             if constexpr (SP2) {
;             PG8_LDB(B0, 0, 0); PG8_LDB(B1, 0, 1); PG8_SCHED; PG8_LDA(At, 0, 0); PG8_STAGE(PG8_SA(1, 1), a1 + hstep, voffA);
;             PG8_WAIT_V(8); PG8_WAIT_L(0); PG8_BAR; PG8_MMA(0, 0, At, B0); PG8_MMA(0, 1, At, B1); PG8_BAR; PG8_SCHED;
;             PG8_LDA(At, 0, 1); PG8_STAGE(PG8_SB(0, 0), b2, voffB); PG8_STAGE(PG8_SB(0, 1), b2 + hstep, voffB); PG8_STAGE(PG8_SA(0, 0), a2, voffA);
;             PG8_WAIT_V(8); PG8_WAIT_L(0); PG8_BAR; PG8_MMA(1, 0, At, B0); PG8_MMA(1, 1, At, B1); PG8_BAR; PG8_SCHED;
.LBB0_68:
	ds_read_b128 v[128:131], v203
	ds_read_b128 v[132:135], v203 offset:1024
	ds_read_b128 v[136:139], v203 offset:2048
	ds_read_b128 v[140:143], v203 offset:3072
	ds_read_b128 v[144:147], v204
	ds_read_b128 v[148:151], v204 offset:1024
	ds_read_b128 v[180:183], v204 offset:2048
	ds_read_b128 v[184:187], v204 offset:3072
	s_add_u32 s30, s82, 0xfff80080
	s_addc_u32 s31, s83, -1
	s_cmp_eq_u32 s29, 28
	s_cselect_b32 s87, s1, s31
	s_cselect_b32 s86, s75, s30
	s_cselect_b32 s85, s73, vcc_hi
	s_cselect_b32 s84, s81, vcc_lo
	s_add_i32 m0, s94, 0xc000
	ds_read_b128 v[206:209], v205
	ds_read_b128 v[210:213], v205 offset:1024
	ds_read_b128 v[214:217], v205 offset:2048
	ds_read_b128 v[218:221], v205 offset:3072
	ds_read_b128 v[222:225], v205 offset:4096
	ds_read_b128 v[226:229], v205 offset:5120
	ds_read_b128 v[230:233], v205 offset:6144
	ds_read_b128 v[234:237], v205 offset:7168
	global_load_lds_dwordx4 v170, s[82:83]
	s_add_i32 m0, s94, 0xe000
	s_nop 0
	global_load_lds_dwordx4 v172, s[82:83]
	s_waitcnt vmcnt(8)
	s_waitcnt lgkmcnt(0)
	s_barrier
	v_mfma_f32_16x16x32_bf16 v[124:127], v[128:131], v[206:209], v[124:127]
	v_mfma_f32_16x16x32_bf16 v[120:123], v[136:139], v[206:209], v[120:123]
	v_mfma_f32_16x16x32_bf16 v[116:119], v[128:131], v[214:217], v[116:119]
	v_mfma_f32_16x16x32_bf16 v[112:115], v[136:139], v[214:217], v[112:115]
	v_mfma_f32_16x16x32_bf16 v[108:111], v[128:131], v[222:225], v[108:111]
	v_mfma_f32_16x16x32_bf16 v[104:107], v[136:139], v[222:225], v[104:107]
	v_mfma_f32_16x16x32_bf16 v[100:103], v[128:131], v[230:233], v[100:103]
	v_mfma_f32_16x16x32_bf16 v[96:99], v[136:139], v[230:233], v[96:99]
	v_mfma_f32_16x16x32_bf16 v[124:127], v[132:135], v[210:213], v[124:127]
	v_mfma_f32_16x16x32_bf16 v[120:123], v[140:143], v[210:213], v[120:123]
	v_mfma_f32_16x16x32_bf16 v[116:119], v[132:135], v[218:221], v[116:119]
	v_mfma_f32_16x16x32_bf16 v[112:115], v[140:143], v[218:221], v[112:115]
	v_mfma_f32_16x16x32_bf16 v[108:111], v[132:135], v[226:229], v[108:111]
	v_mfma_f32_16x16x32_bf16 v[104:107], v[140:143], v[226:229], v[104:107]
	v_mfma_f32_16x16x32_bf16 v[100:103], v[132:135], v[234:237], v[100:103]
	v_mfma_f32_16x16x32_bf16 v[96:99], v[140:143], v[234:237], v[96:99]
	v_mfma_f32_16x16x32_bf16 v[68:71], v[144:147], v[206:209], v[68:71]
	v_mfma_f32_16x16x32_bf16 v[64:67], v[180:183], v[206:209], v[64:67]
	v_mfma_f32_16x16x32_bf16 v[52:55], v[144:147], v[214:217], v[52:55]
	v_mfma_f32_16x16x32_bf16 v[48:51], v[180:183], v[214:217], v[48:51]
	v_mfma_f32_16x16x32_bf16 v[44:47], v[144:147], v[222:225], v[44:47]
	v_mfma_f32_16x16x32_bf16 v[40:43], v[180:183], v[222:225], v[40:43]
	v_mfma_f32_16x16x32_bf16 v[36:39], v[144:147], v[230:233], v[36:39]
	v_mfma_f32_16x16x32_bf16 v[32:35], v[180:183], v[230:233], v[32:35]
	v_mfma_f32_16x16x32_bf16 v[68:71], v[148:151], v[210:213], v[68:71]
	v_mfma_f32_16x16x32_bf16 v[64:67], v[184:187], v[210:213], v[64:67]
	v_mfma_f32_16x16x32_bf16 v[52:55], v[148:151], v[218:221], v[52:55]
	v_mfma_f32_16x16x32_bf16 v[48:51], v[184:187], v[218:221], v[48:51]
	v_mfma_f32_16x16x32_bf16 v[44:47], v[148:151], v[226:229], v[44:47]
	v_mfma_f32_16x16x32_bf16 v[40:43], v[184:187], v[226:229], v[40:43]
	v_mfma_f32_16x16x32_bf16 v[36:39], v[148:151], v[234:237], v[36:39]
	v_mfma_f32_16x16x32_bf16 v[32:35], v[184:187], v[234:237], v[32:35]
	s_barrier
	s_add_i32 s30, s47, s92
	s_mov_b32 m0, s30
	ds_read_b128 v[206:209], v205 offset:16384
	ds_read_b128 v[210:213], v205 offset:17408
	ds_read_b128 v[214:217], v205 offset:18432
	ds_read_b128 v[218:221], v205 offset:19456
	ds_read_b128 v[222:225], v205 offset:20480
	ds_read_b128 v[226:229], v205 offset:21504
	ds_read_b128 v[230:233], v205 offset:22528
	ds_read_b128 v[234:237], v205 offset:23552
	global_load_lds_dwordx4 v158, s[84:85]
	s_add_i32 m0, s30, 0x2000
	s_add_u32 s30, s84, 0x80000
	s_addc_u32 s31, s85, 0
	s_add_i32 s89, s33, s92
	global_load_lds_dwordx4 v154, s[84:85]
	s_mov_b32 m0, s89
	s_nop 0
	global_load_lds_dwordx4 v158, s[30:31]
	s_add_i32 m0, s89, 0x2000
	s_nop 0
	global_load_lds_dwordx4 v154, s[30:31]
	s_mov_b32 m0, s94
	s_nop 0
	global_load_lds_dwordx4 v160, s[86:87]
	s_mov_b32 m0, s95
	s_nop 0
	global_load_lds_dwordx4 v156, s[86:87]
	s_waitcnt vmcnt(8)
	s_waitcnt lgkmcnt(0)
	s_barrier
	v_mfma_f32_16x16x32_bf16 v[92:95], v[128:131], v[206:209], v[92:95]
	v_mfma_f32_16x16x32_bf16 v[88:91], v[136:139], v[206:209], v[88:91]
	v_mfma_f32_16x16x32_bf16 v[84:87], v[128:131], v[214:217], v[84:87]
	v_mfma_f32_16x16x32_bf16 v[80:83], v[136:139], v[214:217], v[80:83]
	v_mfma_f32_16x16x32_bf16 v[76:79], v[128:131], v[222:225], v[76:79]
	v_mfma_f32_16x16x32_bf16 v[72:75], v[136:139], v[222:225], v[72:75]
	v_mfma_f32_16x16x32_bf16 v[60:63], v[128:131], v[230:233], v[60:63]
	v_mfma_f32_16x16x32_bf16 v[56:59], v[136:139], v[230:233], v[56:59]
	v_mfma_f32_16x16x32_bf16 v[92:95], v[132:135], v[210:213], v[92:95]
	v_mfma_f32_16x16x32_bf16 v[88:91], v[140:143], v[210:213], v[88:91]
	v_mfma_f32_16x16x32_bf16 v[84:87], v[132:135], v[218:221], v[84:87]
	v_mfma_f32_16x16x32_bf16 v[80:83], v[140:143], v[218:221], v[80:83]
	v_mfma_f32_16x16x32_bf16 v[76:79], v[132:135], v[226:229], v[76:79]
	v_mfma_f32_16x16x32_bf16 v[72:75], v[140:143], v[226:229], v[72:75]
	v_mfma_f32_16x16x32_bf16 v[60:63], v[132:135], v[234:237], v[60:63]
	v_mfma_f32_16x16x32_bf16 v[56:59], v[140:143], v[234:237], v[56:59]
	v_mfma_f32_16x16x32_bf16 v[28:31], v[144:147], v[206:209], v[28:31]
	v_mfma_f32_16x16x32_bf16 v[24:27], v[180:183], v[206:209], v[24:27]
	v_mfma_f32_16x16x32_bf16 v[20:23], v[144:147], v[214:217], v[20:23]
	v_mfma_f32_16x16x32_bf16 v[16:19], v[180:183], v[214:217], v[16:19]
	v_mfma_f32_16x16x32_bf16 v[12:15], v[144:147], v[222:225], v[12:15]
	v_mfma_f32_16x16x32_bf16 v[8:11], v[180:183], v[222:225], v[8:11]
	v_mfma_f32_16x16x32_bf16 v[4:7], v[144:147], v[230:233], v[4:7]
	v_mfma_f32_16x16x32_bf16 v[0:3], v[180:183], v[230:233], v[0:3]
	v_mfma_f32_16x16x32_bf16 v[28:31], v[148:151], v[210:213], v[28:31]
	v_mfma_f32_16x16x32_bf16 v[24:27], v[184:187], v[210:213], v[24:27]
	v_mfma_f32_16x16x32_bf16 v[20:23], v[148:151], v[218:221], v[20:23]
	v_mfma_f32_16x16x32_bf16 v[16:19], v[184:187], v[218:221], v[16:19]
	v_mfma_f32_16x16x32_bf16 v[12:15], v[148:151], v[226:229], v[12:15]
	v_mfma_f32_16x16x32_bf16 v[8:11], v[184:187], v[226:229], v[8:11]
	v_mfma_f32_16x16x32_bf16 v[4:7], v[148:151], v[234:237], v[4:7]
	v_mfma_f32_16x16x32_bf16 v[0:3], v[184:187], v[234:237], v[0:3]
	s_barrier
; #define PG8_STAGE(bufoff, gbase, voff) do { _Pragma("unroll") for (int _i = 0; _i < 2; ++_i) \
;         __builtin_amdgcn_global_load_lds((const unsigned*)((const char*)(gbase) + (voff)[_i]), (PG8_LAS unsigned*)(lds + (bufoff) + ldsw + _i * 8192), 16, 0, 0); } while (0)
; #define PG8_LDA(dst, b, h) do { _Pragma("unroll") for (int m = 0; m < 4; ++m) _Pragma("unroll") for (int k = 0; k < 2; ++k) dst[m][k] = *(const PG8_LAS bf16x8*)(lds + PG8_SA(b, h) + aoff + m * 2048 + k * 1024); } while (0)
; #define PG8_LDB(dst, b, h) do { _Pragma("unroll") for (int n = 0; n < 2; ++n) _Pragma("unroll") for (int k = 0; k < 2; ++k) dst[n][k] = *(const PG8_LAS bf16x8*)(lds + PG8_SB(b, h) + boff + n * 2048 + k * 1024); } while (0)
; #define PG8_MMA(ai, bj, At, Bt) do { __builtin_amdgcn_s_setprio(1); _Pragma("unroll") for (int m = 0; m < 4; ++m) _Pragma("unroll") for (int n = 0; n < 2; ++n) _Pragma("unroll") for (int k = 0; k < 2; ++k) \
;         acc[ai][bj][m][n] = __builtin_amdgcn_mfma_f32_16x16x32_bf16(Bt[n][k], At[m][k], acc[ai][bj][m][n], 0, 0, 0); __builtin_amdgcn_s_setprio(0); } while (0)
; #define PG8_WAIT_V(n) asm volatile("s_waitcnt vmcnt(" #n ")" ::: "memory")
; #define PG8_WAIT_L(n) asm volatile("s_waitcnt lgkmcnt(" #n ")" ::: "memory")
; #define PG8_BAR __builtin_amdgcn_s_barrier()
; #define PG8_SCHED __builtin_amdgcn_sched_barrier(0)
; template <class Epi, class Sched, bool ALIGN_EPI = false, bool SP2 = false>
; __device__ __forceinline__ void gemm_phase(PG8_LAS unsigned char* lds, const Gemm g, const Sched& S, const Epi& E) {
;     ...
;         for (int t = 0; t < nt; t += 2) {
;             const bool last = (t == nt - 2);
;             const char* a1 = cA + (size_t)(t + 1) * kstep;
;             const char* a2 = last ? nA : cA + (size_t)(t + 2) * kstep; const char* b2 = last ? nB : cB + (size_t)(t + 2) * kstep;
;     ...
;             PG8_LDB(B0, 1, 0); PG8_LDB(B1, 1, 1); PG8_SCHED; PG8_LDA(At, 1, 0); PG8_STAGE(PG8_SA(0, 1), a2 + hstep, voffA);
;             PG8_WAIT_V(8); PG8_WAIT_L(0); PG8_BAR; PG8_MMA(0, 0, At, B0); PG8_MMA(0, 1, At, B1); PG8_BAR; PG8_SCHED;
;             PG8_LDA(At, 1, 1); PG8_STAGE(PG8_SB(1, 0), b3, voffB); PG8_STAGE(PG8_SB(1, 1), b3 + hstep, voffB); PG8_STAGE(PG8_SA(1, 0), a3, voffA);
;             PG8_WAIT_V(8); PG8_WAIT_L(0); PG8_BAR; PG8_MMA(1, 0, At, B0); PG8_MMA(1, 1, At, B1); PG8_BAR; PG8_SCHED;
	s_add_i32 s89, 0, 0x18000
	s_add_i32 s54, 0, 0x1c000
	v_add_u32_e32 v140, s89, v190
	v_add_u32_e32 v162, s54, v190
	ds_read_b128 v[128:131], v140
	ds_read_b128 v[132:135], v140 offset:1024
	ds_read_b128 v[136:139], v140 offset:2048
	ds_read_b128 v[140:143], v140 offset:3072
	ds_read_b128 v[144:147], v162
	ds_read_b128 v[148:151], v162 offset:1024
	ds_read_b128 v[180:183], v162 offset:2048
	ds_read_b128 v[184:187], v162 offset:3072
	s_add_u32 s30, s86, 0x80000
	s_addc_u32 s31, s87, 0
	s_mov_b32 m0, s96
	ds_read_b128 v[206:209], v205 offset:32768
	ds_read_b128 v[210:213], v205 offset:33792
	ds_read_b128 v[214:217], v205 offset:34816
	ds_read_b128 v[218:221], v205 offset:35840
	ds_read_b128 v[222:225], v205 offset:36864
	ds_read_b128 v[226:229], v205 offset:37888
	ds_read_b128 v[230:233], v205 offset:38912
	ds_read_b128 v[234:237], v205 offset:39936
	global_load_lds_dwordx4 v160, s[30:31]
	s_mov_b32 m0, s97
	s_nop 0
	global_load_lds_dwordx4 v156, s[30:31]
	s_waitcnt vmcnt(8)
	s_waitcnt lgkmcnt(0)
	s_barrier
	v_mfma_f32_16x16x32_bf16 v[124:127], v[128:131], v[206:209], v[124:127]
	v_mfma_f32_16x16x32_bf16 v[120:123], v[136:139], v[206:209], v[120:123]
	v_mfma_f32_16x16x32_bf16 v[116:119], v[128:131], v[214:217], v[116:119]
	v_mfma_f32_16x16x32_bf16 v[112:115], v[136:139], v[214:217], v[112:115]
	v_mfma_f32_16x16x32_bf16 v[108:111], v[128:131], v[222:225], v[108:111]
	v_mfma_f32_16x16x32_bf16 v[104:107], v[136:139], v[222:225], v[104:107]
	v_mfma_f32_16x16x32_bf16 v[100:103], v[128:131], v[230:233], v[100:103]
	v_mfma_f32_16x16x32_bf16 v[96:99], v[136:139], v[230:233], v[96:99]
	v_mfma_f32_16x16x32_bf16 v[124:127], v[132:135], v[210:213], v[124:127]
	v_mfma_f32_16x16x32_bf16 v[120:123], v[140:143], v[210:213], v[120:123]
	v_mfma_f32_16x16x32_bf16 v[116:119], v[132:135], v[218:221], v[116:119]
	v_mfma_f32_16x16x32_bf16 v[112:115], v[140:143], v[218:221], v[112:115]
	v_mfma_f32_16x16x32_bf16 v[108:111], v[132:135], v[226:229], v[108:111]
	v_mfma_f32_16x16x32_bf16 v[104:107], v[140:143], v[226:229], v[104:107]
	v_mfma_f32_16x16x32_bf16 v[100:103], v[132:135], v[234:237], v[100:103]
	v_mfma_f32_16x16x32_bf16 v[96:99], v[140:143], v[234:237], v[96:99]
	v_mfma_f32_16x16x32_bf16 v[68:71], v[144:147], v[206:209], v[68:71]
	v_mfma_f32_16x16x32_bf16 v[64:67], v[180:183], v[206:209], v[64:67]
	v_mfma_f32_16x16x32_bf16 v[52:55], v[144:147], v[214:217], v[52:55]
	v_mfma_f32_16x16x32_bf16 v[48:51], v[180:183], v[214:217], v[48:51]
	v_mfma_f32_16x16x32_bf16 v[44:47], v[144:147], v[222:225], v[44:47]
	v_mfma_f32_16x16x32_bf16 v[40:43], v[180:183], v[222:225], v[40:43]
	v_mfma_f32_16x16x32_bf16 v[36:39], v[144:147], v[230:233], v[36:39]
	v_mfma_f32_16x16x32_bf16 v[32:35], v[180:183], v[230:233], v[32:35]
	v_mfma_f32_16x16x32_bf16 v[68:71], v[148:151], v[210:213], v[68:71]
	v_mfma_f32_16x16x32_bf16 v[64:67], v[184:187], v[210:213], v[64:67]
	v_mfma_f32_16x16x32_bf16 v[52:55], v[148:151], v[218:221], v[52:55]
	v_mfma_f32_16x16x32_bf16 v[48:51], v[184:187], v[218:221], v[48:51]
	v_mfma_f32_16x16x32_bf16 v[44:47], v[148:151], v[226:229], v[44:47]
	v_mfma_f32_16x16x32_bf16 v[40:43], v[184:187], v[226:229], v[40:43]
	v_mfma_f32_16x16x32_bf16 v[36:39], v[148:151], v[234:237], v[36:39]
	v_mfma_f32_16x16x32_bf16 v[32:35], v[184:187], v[234:237], v[32:35]
	s_barrier
	s_add_i32 s30, s89, s92
	s_mov_b32 m0, s30
	ds_read_b128 v[206:209], v205 offset:49152
	ds_read_b128 v[210:213], v205 offset:50176
	ds_read_b128 v[214:217], v205 offset:51200
	ds_read_b128 v[218:221], v205 offset:52224
	ds_read_b128 v[222:225], v205 offset:53248
	ds_read_b128 v[226:229], v205 offset:54272
	ds_read_b128 v[230:233], v205 offset:55296
	ds_read_b128 v[234:237], v205 offset:56320
	s_add_u32 s62, s84, 0x80
	s_addc_u32 s63, s85, 0
	global_load_lds_dwordx4 v158, s[62:63]
	s_add_i32 m0, s30, 0x2000
	s_add_u32 s30, s84, 0x80080
	s_addc_u32 s31, s85, 0
	s_add_i32 s54, s54, s92
	global_load_lds_dwordx4 v154, s[62:63]
	s_mov_b32 m0, s54
	s_nop 0
	global_load_lds_dwordx4 v158, s[30:31]
	s_add_i32 m0, s54, 0x2000
	s_nop 0
	global_load_lds_dwordx4 v154, s[30:31]
	s_mov_b32 m0, s88
	s_nop 0
	s_add_u32 s62, s86, 0x80
	s_addc_u32 s63, s87, 0
	global_load_lds_dwordx4 v160, s[62:63]
	s_mov_b32 m0, s46
	s_nop 0
	global_load_lds_dwordx4 v156, s[62:63]
	s_waitcnt vmcnt(8)
	s_waitcnt lgkmcnt(0)
	s_barrier
	v_mfma_f32_16x16x32_bf16 v[92:95], v[128:131], v[206:209], v[92:95]
	v_mfma_f32_16x16x32_bf16 v[88:91], v[136:139], v[206:209], v[88:91]
	v_mfma_f32_16x16x32_bf16 v[84:87], v[128:131], v[214:217], v[84:87]
	v_mfma_f32_16x16x32_bf16 v[80:83], v[136:139], v[214:217], v[80:83]
	v_mfma_f32_16x16x32_bf16 v[76:79], v[128:131], v[222:225], v[76:79]
	v_mfma_f32_16x16x32_bf16 v[72:75], v[136:139], v[222:225], v[72:75]
	v_mfma_f32_16x16x32_bf16 v[60:63], v[128:131], v[230:233], v[60:63]
	v_mfma_f32_16x16x32_bf16 v[56:59], v[136:139], v[230:233], v[56:59]
	v_mfma_f32_16x16x32_bf16 v[92:95], v[132:135], v[210:213], v[92:95]
	v_mfma_f32_16x16x32_bf16 v[88:91], v[140:143], v[210:213], v[88:91]
	v_mfma_f32_16x16x32_bf16 v[84:87], v[132:135], v[218:221], v[84:87]
	v_mfma_f32_16x16x32_bf16 v[80:83], v[140:143], v[218:221], v[80:83]
	v_mfma_f32_16x16x32_bf16 v[76:79], v[132:135], v[226:229], v[76:79]
	v_mfma_f32_16x16x32_bf16 v[72:75], v[140:143], v[226:229], v[72:75]
	v_mfma_f32_16x16x32_bf16 v[60:63], v[132:135], v[234:237], v[60:63]
	v_mfma_f32_16x16x32_bf16 v[56:59], v[140:143], v[234:237], v[56:59]
	v_mfma_f32_16x16x32_bf16 v[28:31], v[144:147], v[206:209], v[28:31]
	v_mfma_f32_16x16x32_bf16 v[24:27], v[180:183], v[206:209], v[24:27]
	v_mfma_f32_16x16x32_bf16 v[20:23], v[144:147], v[214:217], v[20:23]
	v_mfma_f32_16x16x32_bf16 v[16:19], v[180:183], v[214:217], v[16:19]
	v_mfma_f32_16x16x32_bf16 v[12:15], v[144:147], v[222:225], v[12:15]
	v_mfma_f32_16x16x32_bf16 v[8:11], v[180:183], v[222:225], v[8:11]
	v_mfma_f32_16x16x32_bf16 v[4:7], v[144:147], v[230:233], v[4:7]
	v_mfma_f32_16x16x32_bf16 v[0:3], v[180:183], v[230:233], v[0:3]
	v_mfma_f32_16x16x32_bf16 v[28:31], v[148:151], v[210:213], v[28:31]
	v_mfma_f32_16x16x32_bf16 v[24:27], v[184:187], v[210:213], v[24:27]
	v_mfma_f32_16x16x32_bf16 v[20:23], v[148:151], v[218:221], v[20:23]
	v_mfma_f32_16x16x32_bf16 v[16:19], v[184:187], v[218:221], v[16:19]
	v_mfma_f32_16x16x32_bf16 v[12:15], v[148:151], v[226:229], v[12:15]
	v_mfma_f32_16x16x32_bf16 v[8:11], v[184:187], v[226:229], v[8:11]
	v_mfma_f32_16x16x32_bf16 v[4:7], v[148:151], v[234:237], v[4:7]
	v_mfma_f32_16x16x32_bf16 v[0:3], v[184:187], v[234:237], v[0:3]
	s_barrier
	s_add_i32 s29, s29, 2
	s_add_u32 s82, s82, 0x100
	s_addc_u32 s83, s83, 0
	s_add_u32 vcc_lo, vcc_lo, 0x100
	s_addc_u32 vcc_hi, vcc_hi, 0
	s_cmp_gt_u32 s29, 29
	s_cbranch_scc0 .LBB0_68
	s_and_b64 vcc, exec, s[64:65]
	s_cbranch_vccz .LBB0_71
	s_barrier

; #define PG8_STAGE(bufoff, gbase, voff) do { _Pragma("unroll") for (int _i = 0; _i < 2; ++_i) \
;         __builtin_amdgcn_global_load_lds((const unsigned*)((const char*)(gbase) + (voff)[_i]), (PG8_LAS unsigned*)(lds + (bufoff) + ldsw + _i * 8192), 16, 0, 0); } while (0)
; #define PG8_LDA(dst, b, h) do { _Pragma("unroll") for (int m = 0; m < 4; ++m) _Pragma("unroll") for (int k = 0; k < 2; ++k) dst[m][k] = *(const PG8_LAS bf16x8*)(lds + PG8_SA(b, h) + aoff + m * 2048 + k * 1024); } while (0)
; #define PG8_LDB(dst, b, h) do { _Pragma("unroll") for (int n = 0; n < 2; ++n) _Pragma("unroll") for (int k = 0; k < 2; ++k) dst[n][k] = *(const PG8_LAS bf16x8*)(lds + PG8_SB(b, h) + boff + n * 2048 + k * 1024); } while (0)
; #define PG8_MMA(ai, bj, At, Bt) do { __builtin_amdgcn_s_setprio(1); _Pragma("unroll") for (int m = 0; m < 4; ++m) _Pragma("unroll") for (int n = 0; n < 2; ++n) _Pragma("unroll") for (int k = 0; k < 2; ++k) \
;         acc[ai][bj][m][n] = __builtin_amdgcn_mfma_f32_16x16x32_bf16(Bt[n][k], At[m][k], acc[ai][bj][m][n], 0, 0, 0); __builtin_amdgcn_s_setprio(0); } while (0)
; #define PG8_WAIT_V(n) asm volatile("s_waitcnt vmcnt(" #n ")" ::: "memory")
; #define PG8_WAIT_L(n) asm volatile("s_waitcnt lgkmcnt(" #n ")" ::: "memory")
; template <class Epi, class Sched, bool ALIGN_EPI = false, bool SP2 = false>
; __device__ __forceinline__ void gemm_phase(PG8_LAS unsigned char* lds, const Gemm g, const Sched& S, const Epi& E) {
;     ...
;             const bool last = (t == nt - 2);
;             const char* a1 = cA + (size_t)(t + 1) * kstep;
;             const char* a2 = last ? nA : cA + (size_t)(t + 2) * kstep; const char* b2 = last ? nB : cB + (size_t)(t + 2) * kstep;
;             const char* a3 = a2 + kstep; const char* b3 = b2 + kstep;
;             if (last && has_next) S.a_ready(nxt);
;             if constexpr (SP2) {
;             PG8_LDB(B0, 0, 0); PG8_LDB(B1, 0, 1); PG8_SCHED; PG8_LDA(At, 0, 0); PG8_STAGE(PG8_SA(1, 1), a1 + hstep, voffA);
;             PG8_WAIT_V(8); PG8_WAIT_L(0); PG8_BAR; PG8_MMA(0, 0, At, B0); PG8_MMA(0, 1, At, B1); PG8_BAR; PG8_SCHED;
;             PG8_LDA(At, 0, 1); PG8_STAGE(PG8_SB(0, 0), b2, voffB); PG8_STAGE(PG8_SB(0, 1), b2 + hstep, voffB); PG8_STAGE(PG8_SA(0, 0), a2, voffA);
;             PG8_WAIT_V(8); PG8_WAIT_L(0); PG8_BAR; PG8_MMA(1, 0, At, B0); PG8_MMA(1, 1, At, B1); PG8_BAR; PG8_SCHED;
.LBB0_283:
	ds_read_b128 v[152:155], v149
	ds_read_b128 v[156:159], v149 offset:1024
	ds_read_b128 v[160:163], v149 offset:2048
	ds_read_b128 v[164:167], v149 offset:3072
	ds_read_b128 v[168:171], v150
	ds_read_b128 v[172:175], v150 offset:1024
	ds_read_b128 v[180:183], v150 offset:2048
	ds_read_b128 v[184:187], v150 offset:3072
	s_add_u32 s30, s66, 0xfff80080
	s_addc_u32 s31, s67, -1
	s_cmp_eq_u32 s85, 28
	s_cselect_b32 s71, s59, s31
	s_cselect_b32 s70, s81, s30
	s_cselect_b32 s69, s57, s84
	s_cselect_b32 s68, s82, s83
	s_add_i32 m0, s29, 0xc000
	ds_read_b128 v[188:191], v151
	ds_read_b128 v[192:195], v151 offset:1024
	ds_read_b128 v[196:199], v151 offset:2048
	ds_read_b128 v[200:203], v151 offset:3072
	ds_read_b128 v[204:207], v151 offset:4096
	ds_read_b128 v[208:211], v151 offset:5120
	ds_read_b128 v[212:215], v151 offset:6144
	ds_read_b128 v[216:219], v151 offset:7168
	global_load_lds_dwordx4 v136, s[66:67]
	s_add_i32 m0, s29, 0xe000
	s_nop 0
	global_load_lds_dwordx4 v138, s[66:67]
	s_waitcnt vmcnt(8)
	s_waitcnt lgkmcnt(0)
	s_barrier
	v_mfma_f32_16x16x32_bf16 v[124:127], v[152:155], v[188:191], v[124:127]
	v_mfma_f32_16x16x32_bf16 v[120:123], v[160:163], v[188:191], v[120:123]
	v_mfma_f32_16x16x32_bf16 v[116:119], v[152:155], v[196:199], v[116:119]
	v_mfma_f32_16x16x32_bf16 v[108:111], v[160:163], v[196:199], v[108:111]
	v_mfma_f32_16x16x32_bf16 v[100:103], v[152:155], v[204:207], v[100:103]
	v_mfma_f32_16x16x32_bf16 v[92:95], v[160:163], v[204:207], v[92:95]
	v_mfma_f32_16x16x32_bf16 v[84:87], v[152:155], v[212:215], v[84:87]
	v_mfma_f32_16x16x32_bf16 v[76:79], v[160:163], v[212:215], v[76:79]
	v_mfma_f32_16x16x32_bf16 v[124:127], v[156:159], v[192:195], v[124:127]
	v_mfma_f32_16x16x32_bf16 v[120:123], v[164:167], v[192:195], v[120:123]
	v_mfma_f32_16x16x32_bf16 v[116:119], v[156:159], v[200:203], v[116:119]
	v_mfma_f32_16x16x32_bf16 v[108:111], v[164:167], v[200:203], v[108:111]
	v_mfma_f32_16x16x32_bf16 v[100:103], v[156:159], v[208:211], v[100:103]
	v_mfma_f32_16x16x32_bf16 v[92:95], v[164:167], v[208:211], v[92:95]
	v_mfma_f32_16x16x32_bf16 v[84:87], v[156:159], v[216:219], v[84:87]
	v_mfma_f32_16x16x32_bf16 v[76:79], v[164:167], v[216:219], v[76:79]
	v_mfma_f32_16x16x32_bf16 v[112:115], v[168:171], v[188:191], v[112:115]
	v_mfma_f32_16x16x32_bf16 v[104:107], v[180:183], v[188:191], v[104:107]
	v_mfma_f32_16x16x32_bf16 v[96:99], v[168:171], v[196:199], v[96:99]
	v_mfma_f32_16x16x32_bf16 v[88:91], v[180:183], v[196:199], v[88:91]
	v_mfma_f32_16x16x32_bf16 v[80:83], v[168:171], v[204:207], v[80:83]
	v_mfma_f32_16x16x32_bf16 v[72:75], v[180:183], v[204:207], v[72:75]
	v_mfma_f32_16x16x32_bf16 v[68:71], v[168:171], v[212:215], v[68:71]
	v_mfma_f32_16x16x32_bf16 v[64:67], v[180:183], v[212:215], v[64:67]
	v_mfma_f32_16x16x32_bf16 v[112:115], v[172:175], v[192:195], v[112:115]
	v_mfma_f32_16x16x32_bf16 v[104:107], v[184:187], v[192:195], v[104:107]
	v_mfma_f32_16x16x32_bf16 v[96:99], v[172:175], v[200:203], v[96:99]
	v_mfma_f32_16x16x32_bf16 v[88:91], v[184:187], v[200:203], v[88:91]
	v_mfma_f32_16x16x32_bf16 v[80:83], v[172:175], v[208:211], v[80:83]
	v_mfma_f32_16x16x32_bf16 v[72:75], v[184:187], v[208:211], v[72:75]
	v_mfma_f32_16x16x32_bf16 v[68:71], v[172:175], v[216:219], v[68:71]
	v_mfma_f32_16x16x32_bf16 v[64:67], v[184:187], v[216:219], v[64:67]
	s_barrier
	s_add_i32 s30, s74, s1
	s_mov_b32 m0, s30
	ds_read_b128 v[188:191], v151 offset:16384
	ds_read_b128 v[192:195], v151 offset:17408
	ds_read_b128 v[196:199], v151 offset:18432
	ds_read_b128 v[200:203], v151 offset:19456
	ds_read_b128 v[204:207], v151 offset:20480
	ds_read_b128 v[208:211], v151 offset:21504
	ds_read_b128 v[212:215], v151 offset:22528
	ds_read_b128 v[216:219], v151 offset:23552
	global_load_lds_dwordx4 v130, s[68:69]
	s_add_i32 m0, s30, 0x2000
	s_add_u32 s30, s68, 0x80000
	s_addc_u32 s31, s69, 0
	s_add_i32 s86, s75, s1
	global_load_lds_dwordx4 v134, s[68:69]
	s_mov_b32 m0, s86
	s_nop 0
	global_load_lds_dwordx4 v130, s[30:31]
	s_add_i32 m0, s86, 0x2000
	s_nop 0
	global_load_lds_dwordx4 v134, s[30:31]
	s_mov_b32 m0, s29
	s_nop 0
	global_load_lds_dwordx4 v128, s[70:71]
	s_mov_b32 m0, s33
	s_nop 0
	global_load_lds_dwordx4 v132, s[70:71]
	s_waitcnt vmcnt(8)
	s_waitcnt lgkmcnt(0)
	s_barrier
	v_mfma_f32_16x16x32_bf16 v[60:63], v[152:155], v[188:191], v[60:63]
	v_mfma_f32_16x16x32_bf16 v[56:59], v[160:163], v[188:191], v[56:59]
	v_mfma_f32_16x16x32_bf16 v[52:55], v[152:155], v[196:199], v[52:55]
	v_mfma_f32_16x16x32_bf16 v[44:47], v[160:163], v[196:199], v[44:47]
	v_mfma_f32_16x16x32_bf16 v[36:39], v[152:155], v[204:207], v[36:39]
	v_mfma_f32_16x16x32_bf16 v[28:31], v[160:163], v[204:207], v[28:31]
	v_mfma_f32_16x16x32_bf16 v[20:23], v[152:155], v[212:215], v[20:23]
	v_mfma_f32_16x16x32_bf16 v[12:15], v[160:163], v[212:215], v[12:15]
	v_mfma_f32_16x16x32_bf16 v[60:63], v[156:159], v[192:195], v[60:63]
	v_mfma_f32_16x16x32_bf16 v[56:59], v[164:167], v[192:195], v[56:59]
	v_mfma_f32_16x16x32_bf16 v[52:55], v[156:159], v[200:203], v[52:55]
	v_mfma_f32_16x16x32_bf16 v[44:47], v[164:167], v[200:203], v[44:47]
	v_mfma_f32_16x16x32_bf16 v[36:39], v[156:159], v[208:211], v[36:39]
	v_mfma_f32_16x16x32_bf16 v[28:31], v[164:167], v[208:211], v[28:31]
	v_mfma_f32_16x16x32_bf16 v[20:23], v[156:159], v[216:219], v[20:23]
	v_mfma_f32_16x16x32_bf16 v[12:15], v[164:167], v[216:219], v[12:15]
	v_mfma_f32_16x16x32_bf16 v[48:51], v[168:171], v[188:191], v[48:51]
	v_mfma_f32_16x16x32_bf16 v[40:43], v[180:183], v[188:191], v[40:43]
	v_mfma_f32_16x16x32_bf16 v[32:35], v[168:171], v[196:199], v[32:35]
	v_mfma_f32_16x16x32_bf16 v[24:27], v[180:183], v[196:199], v[24:27]
	v_mfma_f32_16x16x32_bf16 v[16:19], v[168:171], v[204:207], v[16:19]
	v_mfma_f32_16x16x32_bf16 v[8:11], v[180:183], v[204:207], v[8:11]
	v_mfma_f32_16x16x32_bf16 v[4:7], v[168:171], v[212:215], v[4:7]
	v_mfma_f32_16x16x32_bf16 v[0:3], v[180:183], v[212:215], v[0:3]
	v_mfma_f32_16x16x32_bf16 v[48:51], v[172:175], v[192:195], v[48:51]
	v_mfma_f32_16x16x32_bf16 v[40:43], v[184:187], v[192:195], v[40:43]
	v_mfma_f32_16x16x32_bf16 v[32:35], v[172:175], v[200:203], v[32:35]
	v_mfma_f32_16x16x32_bf16 v[24:27], v[184:187], v[200:203], v[24:27]
	v_mfma_f32_16x16x32_bf16 v[16:19], v[172:175], v[208:211], v[16:19]
	v_mfma_f32_16x16x32_bf16 v[8:11], v[184:187], v[208:211], v[8:11]
	v_mfma_f32_16x16x32_bf16 v[4:7], v[172:175], v[216:219], v[4:7]
	v_mfma_f32_16x16x32_bf16 v[0:3], v[184:187], v[216:219], v[0:3]
	s_barrier
; #define PG8_STAGE(bufoff, gbase, voff) do { _Pragma("unroll") for (int _i = 0; _i < 2; ++_i) \
;         __builtin_amdgcn_global_load_lds((const unsigned*)((const char*)(gbase) + (voff)[_i]), (PG8_LAS unsigned*)(lds + (bufoff) + ldsw + _i * 8192), 16, 0, 0); } while (0)
; #define PG8_LDA(dst, b, h) do { _Pragma("unroll") for (int m = 0; m < 4; ++m) _Pragma("unroll") for (int k = 0; k < 2; ++k) dst[m][k] = *(const PG8_LAS bf16x8*)(lds + PG8_SA(b, h) + aoff + m * 2048 + k * 1024); } while (0)
; #define PG8_LDB(dst, b, h) do { _Pragma("unroll") for (int n = 0; n < 2; ++n) _Pragma("unroll") for (int k = 0; k < 2; ++k) dst[n][k] = *(const PG8_LAS bf16x8*)(lds + PG8_SB(b, h) + boff + n * 2048 + k * 1024); } while (0)
; #define PG8_MMA(ai, bj, At, Bt) do { __builtin_amdgcn_s_setprio(1); _Pragma("unroll") for (int m = 0; m < 4; ++m) _Pragma("unroll") for (int n = 0; n < 2; ++n) _Pragma("unroll") for (int k = 0; k < 2; ++k) \
;         acc[ai][bj][m][n] = __builtin_amdgcn_mfma_f32_16x16x32_bf16(Bt[n][k], At[m][k], acc[ai][bj][m][n], 0, 0, 0); __builtin_amdgcn_s_setprio(0); } while (0)
; #define PG8_WAIT_V(n) asm volatile("s_waitcnt vmcnt(" #n ")" ::: "memory")
; #define PG8_WAIT_L(n) asm volatile("s_waitcnt lgkmcnt(" #n ")" ::: "memory")
; #define PG8_BAR __builtin_amdgcn_s_barrier()
; #define PG8_SCHED __builtin_amdgcn_sched_barrier(0)
; template <class Epi, class Sched, bool ALIGN_EPI = false, bool SP2 = false>
; __device__ __forceinline__ void gemm_phase(PG8_LAS unsigned char* lds, const Gemm g, const Sched& S, const Epi& E) {
;     ...
;             PG8_LDB(B0, 1, 0); PG8_LDB(B1, 1, 1); PG8_SCHED; PG8_LDA(At, 1, 0); PG8_STAGE(PG8_SA(0, 1), a2 + hstep, voffA);
;             PG8_WAIT_V(8); PG8_WAIT_L(0); PG8_BAR; PG8_MMA(0, 0, At, B0); PG8_MMA(0, 1, At, B1); PG8_BAR; PG8_SCHED;
;             PG8_LDA(At, 1, 1); PG8_STAGE(PG8_SB(1, 0), b3, voffB); PG8_STAGE(PG8_SB(1, 1), b3 + hstep, voffB); PG8_STAGE(PG8_SA(1, 0), a3, voffA);
;             PG8_WAIT_V(8); PG8_WAIT_L(0); PG8_BAR; PG8_MMA(1, 0, At, B0); PG8_MMA(1, 1, At, B1); PG8_BAR; PG8_SCHED;
	s_add_i32 s86, 0, 0x18000
	s_add_i32 s87, 0, 0x1c000
	v_add_u32_e32 v164, s86, v147
	v_add_u32_e32 v179, s87, v147
	ds_read_b128 v[152:155], v164
	ds_read_b128 v[156:159], v164 offset:1024
	ds_read_b128 v[160:163], v164 offset:2048
	ds_read_b128 v[164:167], v164 offset:3072
	ds_read_b128 v[168:171], v179
	ds_read_b128 v[172:175], v179 offset:1024
	ds_read_b128 v[180:183], v179 offset:2048
	ds_read_b128 v[184:187], v179 offset:3072
	s_add_u32 s30, s70, 0x80000
	s_addc_u32 s31, s71, 0
	s_mov_b32 m0, s46
	ds_read_b128 v[188:191], v151 offset:32768
	ds_read_b128 v[192:195], v151 offset:33792
	ds_read_b128 v[196:199], v151 offset:34816
	ds_read_b128 v[200:203], v151 offset:35840
	ds_read_b128 v[204:207], v151 offset:36864
	ds_read_b128 v[208:211], v151 offset:37888
	ds_read_b128 v[212:215], v151 offset:38912
	ds_read_b128 v[216:219], v151 offset:39936
	global_load_lds_dwordx4 v128, s[30:31]
	s_mov_b32 m0, s47
	s_nop 0
	global_load_lds_dwordx4 v132, s[30:31]
	s_waitcnt vmcnt(8)
	s_waitcnt lgkmcnt(0)
	s_barrier
	v_mfma_f32_16x16x32_bf16 v[124:127], v[152:155], v[188:191], v[124:127]
	v_mfma_f32_16x16x32_bf16 v[120:123], v[160:163], v[188:191], v[120:123]
	v_mfma_f32_16x16x32_bf16 v[116:119], v[152:155], v[196:199], v[116:119]
	v_mfma_f32_16x16x32_bf16 v[108:111], v[160:163], v[196:199], v[108:111]
	v_mfma_f32_16x16x32_bf16 v[100:103], v[152:155], v[204:207], v[100:103]
	v_mfma_f32_16x16x32_bf16 v[92:95], v[160:163], v[204:207], v[92:95]
	v_mfma_f32_16x16x32_bf16 v[84:87], v[152:155], v[212:215], v[84:87]
	v_mfma_f32_16x16x32_bf16 v[76:79], v[160:163], v[212:215], v[76:79]
	v_mfma_f32_16x16x32_bf16 v[124:127], v[156:159], v[192:195], v[124:127]
	v_mfma_f32_16x16x32_bf16 v[120:123], v[164:167], v[192:195], v[120:123]
	v_mfma_f32_16x16x32_bf16 v[116:119], v[156:159], v[200:203], v[116:119]
	v_mfma_f32_16x16x32_bf16 v[108:111], v[164:167], v[200:203], v[108:111]
	v_mfma_f32_16x16x32_bf16 v[100:103], v[156:159], v[208:211], v[100:103]
	v_mfma_f32_16x16x32_bf16 v[92:95], v[164:167], v[208:211], v[92:95]
	v_mfma_f32_16x16x32_bf16 v[84:87], v[156:159], v[216:219], v[84:87]
	v_mfma_f32_16x16x32_bf16 v[76:79], v[164:167], v[216:219], v[76:79]
	v_mfma_f32_16x16x32_bf16 v[112:115], v[168:171], v[188:191], v[112:115]
	v_mfma_f32_16x16x32_bf16 v[104:107], v[180:183], v[188:191], v[104:107]
	v_mfma_f32_16x16x32_bf16 v[96:99], v[168:171], v[196:199], v[96:99]
	v_mfma_f32_16x16x32_bf16 v[88:91], v[180:183], v[196:199], v[88:91]
	v_mfma_f32_16x16x32_bf16 v[80:83], v[168:171], v[204:207], v[80:83]
	v_mfma_f32_16x16x32_bf16 v[72:75], v[180:183], v[204:207], v[72:75]
	v_mfma_f32_16x16x32_bf16 v[68:71], v[168:171], v[212:215], v[68:71]
	v_mfma_f32_16x16x32_bf16 v[64:67], v[180:183], v[212:215], v[64:67]
	v_mfma_f32_16x16x32_bf16 v[112:115], v[172:175], v[192:195], v[112:115]
	v_mfma_f32_16x16x32_bf16 v[104:107], v[184:187], v[192:195], v[104:107]
	v_mfma_f32_16x16x32_bf16 v[96:99], v[172:175], v[200:203], v[96:99]
	v_mfma_f32_16x16x32_bf16 v[88:91], v[184:187], v[200:203], v[88:91]
	v_mfma_f32_16x16x32_bf16 v[80:83], v[172:175], v[208:211], v[80:83]
	v_mfma_f32_16x16x32_bf16 v[72:75], v[184:187], v[208:211], v[72:75]
	v_mfma_f32_16x16x32_bf16 v[68:71], v[172:175], v[216:219], v[68:71]
	v_mfma_f32_16x16x32_bf16 v[64:67], v[184:187], v[216:219], v[64:67]
	s_barrier
	s_add_i32 s30, s86, s1
	s_mov_b32 m0, s30
	ds_read_b128 v[188:191], v151 offset:49152
	ds_read_b128 v[192:195], v151 offset:50176
	ds_read_b128 v[196:199], v151 offset:51200
	ds_read_b128 v[200:203], v151 offset:52224
	ds_read_b128 v[204:207], v151 offset:53248
	ds_read_b128 v[208:211], v151 offset:54272
	ds_read_b128 v[212:215], v151 offset:55296
	ds_read_b128 v[216:219], v151 offset:56320
	s_add_u32 s8, s68, 0x80
	s_addc_u32 s9, s69, 0
	global_load_lds_dwordx4 v130, s[8:9]
	s_add_i32 m0, s30, 0x2000
	s_add_u32 s30, s68, 0x80080
	s_addc_u32 s31, s69, 0
	s_add_i32 s68, s87, s1
	global_load_lds_dwordx4 v134, s[8:9]
	s_mov_b32 m0, s68
	s_nop 0
	global_load_lds_dwordx4 v130, s[30:31]
	s_add_i32 m0, s68, 0x2000
	s_nop 0
	global_load_lds_dwordx4 v134, s[30:31]
	s_mov_b32 m0, s72
	s_nop 0
	s_add_u32 s8, s70, 0x80
	s_addc_u32 s9, s71, 0
	global_load_lds_dwordx4 v128, s[8:9]
	s_mov_b32 m0, s73
	s_nop 0
	global_load_lds_dwordx4 v132, s[8:9]
	s_waitcnt vmcnt(8)
	s_waitcnt lgkmcnt(0)
	s_barrier
	v_mfma_f32_16x16x32_bf16 v[60:63], v[152:155], v[188:191], v[60:63]
	v_mfma_f32_16x16x32_bf16 v[56:59], v[160:163], v[188:191], v[56:59]
	v_mfma_f32_16x16x32_bf16 v[52:55], v[152:155], v[196:199], v[52:55]
	v_mfma_f32_16x16x32_bf16 v[44:47], v[160:163], v[196:199], v[44:47]
	v_mfma_f32_16x16x32_bf16 v[36:39], v[152:155], v[204:207], v[36:39]
	v_mfma_f32_16x16x32_bf16 v[28:31], v[160:163], v[204:207], v[28:31]
	v_mfma_f32_16x16x32_bf16 v[20:23], v[152:155], v[212:215], v[20:23]
	v_mfma_f32_16x16x32_bf16 v[12:15], v[160:163], v[212:215], v[12:15]
	v_mfma_f32_16x16x32_bf16 v[60:63], v[156:159], v[192:195], v[60:63]
	v_mfma_f32_16x16x32_bf16 v[56:59], v[164:167], v[192:195], v[56:59]
	v_mfma_f32_16x16x32_bf16 v[52:55], v[156:159], v[200:203], v[52:55]
	v_mfma_f32_16x16x32_bf16 v[44:47], v[164:167], v[200:203], v[44:47]
	v_mfma_f32_16x16x32_bf16 v[36:39], v[156:159], v[208:211], v[36:39]
	v_mfma_f32_16x16x32_bf16 v[28:31], v[164:167], v[208:211], v[28:31]
	v_mfma_f32_16x16x32_bf16 v[20:23], v[156:159], v[216:219], v[20:23]
	v_mfma_f32_16x16x32_bf16 v[12:15], v[164:167], v[216:219], v[12:15]
	v_mfma_f32_16x16x32_bf16 v[48:51], v[168:171], v[188:191], v[48:51]
	v_mfma_f32_16x16x32_bf16 v[40:43], v[180:183], v[188:191], v[40:43]
	v_mfma_f32_16x16x32_bf16 v[32:35], v[168:171], v[196:199], v[32:35]
	v_mfma_f32_16x16x32_bf16 v[24:27], v[180:183], v[196:199], v[24:27]
	v_mfma_f32_16x16x32_bf16 v[16:19], v[168:171], v[204:207], v[16:19]
	v_mfma_f32_16x16x32_bf16 v[8:11], v[180:183], v[204:207], v[8:11]
	v_mfma_f32_16x16x32_bf16 v[4:7], v[168:171], v[212:215], v[4:7]
	v_mfma_f32_16x16x32_bf16 v[0:3], v[180:183], v[212:215], v[0:3]
	v_mfma_f32_16x16x32_bf16 v[48:51], v[172:175], v[192:195], v[48:51]
	v_mfma_f32_16x16x32_bf16 v[40:43], v[184:187], v[192:195], v[40:43]
	v_mfma_f32_16x16x32_bf16 v[32:35], v[172:175], v[200:203], v[32:35]
	v_mfma_f32_16x16x32_bf16 v[24:27], v[184:187], v[200:203], v[24:27]
	v_mfma_f32_16x16x32_bf16 v[16:19], v[172:175], v[208:211], v[16:19]
	v_mfma_f32_16x16x32_bf16 v[8:11], v[184:187], v[208:211], v[8:11]
	v_mfma_f32_16x16x32_bf16 v[4:7], v[172:175], v[216:219], v[4:7]
	v_mfma_f32_16x16x32_bf16 v[0:3], v[184:187], v[216:219], v[0:3]
	s_barrier
; __device__ __forceinline__ unsigned cvt_pk_bf16(float lo, float hi) { unsigned r; asm volatile("v_cvt_pk_bf16_f32 %0, %1, %2" : "=v"(r) : "v"(lo), "v"(hi)); return r; }
; #define PG8_WAIT_V(n) asm volatile("s_waitcnt vmcnt(" #n ")" ::: "memory")
; #define PG8_BAR __builtin_amdgcn_s_barrier()
;     __device__ __forceinline__ void operator()(const f32x4 (&acc)[2][2][4][2], const Unit& u, int wr, int wc, int fr, int fq) const {
;         const int row0 = u.pm * BM + wr * 64 + fr; const int col0 = u.pn * BM + wc * 32 + 8 * fq;
; #pragma unroll
;         for (int ai = 0; ai < 2; ++ai)
; #pragma unroll
;             for (int m = 0; m < 4; ++m) { bf16_t* rowp = O + (size_t)(row0 + ai * HALF + m * 16) * ldc + col0;
; #pragma unroll
;                 for (int bj = 0; bj < 2; ++bj) { const f32x4 v0 = acc[ai][bj][m][0], v1 = acc[ai][bj][m][1];
;                     u32x4 w; w.x = cvt_pk_bf16(v0[0], v0[1]); w.y = cvt_pk_bf16(v0[2], v0[3]); w.z = cvt_pk_bf16(v1[0], v1[1]); w.w = cvt_pk_bf16(v1[2], v1[3]);
;                     *(u32x4*)(rowp + bj * HALF) = w; } }
; template <class Epi, class Sched, bool ALIGN_EPI = false, bool SP2 = false>
; __device__ __forceinline__ void gemm_phase(PG8_LAS unsigned char* lds, const Gemm g, const Sched& S, const Epi& E) {
;     ...
;         if constexpr (!Epi::AFTER_DRAIN) { E(acc, cur, wr, wc, fr, fq); S.done(cur); }
;         if (!has_next) break;
; #pragma unroll
;         for (int a = 0; a < 2; ++a)
; #pragma unroll
;             for (int b = 0; b < 2; ++b)
; #pragma unroll
;                 for (int m = 0; m < 4; ++m)
; #pragma unroll
;                     for (int n = 0; n < 2; ++n) acc[a][b][m][n] = (f32x4){0.f, 0.f, 0.f, 0.f};
;         cur = nxt; cA = nA; cB = nB; ++ui;
;         if constexpr (ALIGN_EPI) { if (wr == 1) PG8_BAR; }
;     }
;     PG8_WAIT_V(0);
;     if constexpr (!ALIGN_EPI) { if (wr == 0) PG8_BAR; }
	s_add_i32 s85, s85, 2
	s_add_u32 s66, s66, 0x100
	s_addc_u32 s67, s67, 0
	s_add_u32 s83, s83, 0x100
	s_addc_u32 s84, s84, 0
	s_cmp_gt_u32 s85, 29
	s_cbranch_scc0 .LBB0_283
	v_lshl_add_u32 v152, s64, 8, v146
	v_lshl_or_b32 v144, s80, 8, v148
	v_ashrrev_i32_e32 v153, 31, v152
	v_ashrrev_i32_e32 v145, 31, v144
	v_lshlrev_b64 v[154:155], 12, v[152:153]
	v_lshl_add_u64 v[154:155], s[18:19], 0, v[154:155]
	v_lshlrev_b64 v[156:157], 1, v[144:145]
	v_lshl_add_u64 v[144:145], v[154:155], 0, v[156:157]
	v_cvt_pk_bf16_f32 v124, v124, v125
	v_cvt_pk_bf16_f32 v125, v126, v127
	v_cvt_pk_bf16_f32 v126, v120, v121
	v_cvt_pk_bf16_f32 v127, v122, v123
	global_store_dwordx4 v[144:145], v[124:127], off
	v_cvt_pk_bf16_f32 v112, v112, v113
	v_cvt_pk_bf16_f32 v113, v114, v115
	v_cvt_pk_bf16_f32 v114, v104, v105
	v_or_b32_e32 v104, 16, v152
	v_ashrrev_i32_e32 v105, 31, v104
	v_lshlrev_b64 v[104:105], 12, v[104:105]
	v_lshl_add_u64 v[104:105], s[18:19], 0, v[104:105]
	v_cvt_pk_bf16_f32 v115, v106, v107
	global_store_dwordx4 v[144:145], v[112:115], off offset:256
	s_mov_b32 s80, s56
	s_mov_b32 s64, s58
	v_lshl_add_u64 v[112:113], v[104:105], 0, v[156:157]
	v_cvt_pk_bf16_f32 v104, v116, v117
	v_cvt_pk_bf16_f32 v105, v118, v119
	v_cvt_pk_bf16_f32 v106, v108, v109
	v_cvt_pk_bf16_f32 v107, v110, v111
	global_store_dwordx4 v[112:113], v[104:107], off
	v_cvt_pk_bf16_f32 v96, v96, v97
	v_cvt_pk_bf16_f32 v97, v98, v99
	v_cvt_pk_bf16_f32 v98, v88, v89
	v_or_b32_e32 v88, 32, v152
	v_ashrrev_i32_e32 v89, 31, v88
	v_lshlrev_b64 v[88:89], 12, v[88:89]
	v_lshl_add_u64 v[88:89], s[18:19], 0, v[88:89]
	v_cvt_pk_bf16_f32 v99, v90, v91
	global_store_dwordx4 v[112:113], v[96:99], off offset:256
	s_mov_b64 s[68:69], s[62:63]
	s_mov_b64 s[66:67], s[60:61]
	v_lshl_add_u64 v[96:97], v[88:89], 0, v[156:157]
	v_cvt_pk_bf16_f32 v88, v100, v101
	v_cvt_pk_bf16_f32 v89, v102, v103
	v_cvt_pk_bf16_f32 v90, v92, v93
	v_cvt_pk_bf16_f32 v91, v94, v95
	global_store_dwordx4 v[96:97], v[88:91], off
	v_cvt_pk_bf16_f32 v80, v80, v81
	v_cvt_pk_bf16_f32 v81, v82, v83
	v_cvt_pk_bf16_f32 v82, v72, v73
	v_or_b32_e32 v72, 48, v152
	v_ashrrev_i32_e32 v73, 31, v72
	v_lshlrev_b64 v[72:73], 12, v[72:73]
	v_lshl_add_u64 v[72:73], s[18:19], 0, v[72:73]
	v_cvt_pk_bf16_f32 v83, v74, v75
	global_store_dwordx4 v[96:97], v[80:83], off offset:256
	s_nop 1
	v_lshl_add_u64 v[80:81], v[72:73], 0, v[156:157]
	v_cvt_pk_bf16_f32 v72, v84, v85
	v_cvt_pk_bf16_f32 v73, v86, v87
	v_cvt_pk_bf16_f32 v74, v76, v77
	v_cvt_pk_bf16_f32 v75, v78, v79
	global_store_dwordx4 v[80:81], v[72:75], off
	v_cvt_pk_bf16_f32 v68, v68, v69
	v_cvt_pk_bf16_f32 v69, v70, v71
	v_cvt_pk_bf16_f32 v70, v64, v65
	v_cvt_pk_bf16_f32 v71, v66, v67
	global_store_dwordx4 v[80:81], v[68:71], off offset:256
	v_cvt_pk_bf16_f32 v60, v60, v61
	v_cvt_pk_bf16_f32 v61, v62, v63
	v_cvt_pk_bf16_f32 v62, v56, v57
	v_add_co_u32_e32 v56, vcc, s76, v144
	v_lshl_add_u64 v[64:65], v[144:145], 0, s[6:7]
	s_nop 0
	v_addc_co_u32_e32 v57, vcc, 0, v145, vcc
	v_cvt_pk_bf16_f32 v63, v58, v59
	global_store_dwordx4 v[56:57], v[60:63], off
	v_cvt_pk_bf16_f32 v48, v48, v49
	v_cvt_pk_bf16_f32 v49, v50, v51
	v_cvt_pk_bf16_f32 v50, v40, v41
	v_cvt_pk_bf16_f32 v51, v42, v43
	global_store_dwordx4 v[64:65], v[48:51], off offset:256
	v_cvt_pk_bf16_f32 v40, v52, v53
	v_cvt_pk_bf16_f32 v41, v54, v55
	v_cvt_pk_bf16_f32 v42, v44, v45
	v_add_co_u32_e32 v44, vcc, s77, v144
	s_nop 0
	v_lshl_add_u64 v[48:49], v[144:145], 0, s[10:11]
	v_addc_co_u32_e32 v45, vcc, 0, v145, vcc
	v_cvt_pk_bf16_f32 v43, v46, v47
	global_store_dwordx4 v[44:45], v[40:43], off
	v_cvt_pk_bf16_f32 v32, v32, v33
	v_cvt_pk_bf16_f32 v33, v34, v35
	v_cvt_pk_bf16_f32 v34, v24, v25
	v_cvt_pk_bf16_f32 v35, v26, v27
	global_store_dwordx4 v[48:49], v[32:35], off offset:256
	v_cvt_pk_bf16_f32 v24, v36, v37
	v_cvt_pk_bf16_f32 v25, v38, v39
	v_cvt_pk_bf16_f32 v26, v28, v29
	v_add_co_u32_e32 v28, vcc, s78, v144
	s_nop 0
	v_lshl_add_u64 v[32:33], v[144:145], 0, s[36:37]
	v_addc_co_u32_e32 v29, vcc, 0, v145, vcc
	v_cvt_pk_bf16_f32 v27, v30, v31
	global_store_dwordx4 v[28:29], v[24:27], off
	v_cvt_pk_bf16_f32 v16, v16, v17
	v_cvt_pk_bf16_f32 v17, v18, v19
	v_cvt_pk_bf16_f32 v18, v8, v9
	v_cvt_pk_bf16_f32 v19, v10, v11
	global_store_dwordx4 v[32:33], v[16:19], off offset:256
	v_cvt_pk_bf16_f32 v8, v20, v21
	v_cvt_pk_bf16_f32 v9, v22, v23
	v_cvt_pk_bf16_f32 v10, v12, v13
	v_add_co_u32_e32 v12, vcc, s79, v144
	s_nop 0
	v_lshl_add_u64 v[16:17], v[144:145], 0, s[54:55]
	v_addc_co_u32_e32 v13, vcc, 0, v145, vcc
	s_and_b64 vcc, exec, s[4:5]
	v_cvt_pk_bf16_f32 v11, v14, v15
	global_store_dwordx4 v[12:13], v[8:11], off
	v_cvt_pk_bf16_f32 v4, v4, v5
	v_cvt_pk_bf16_f32 v5, v6, v7
	v_cvt_pk_bf16_f32 v6, v0, v1
	v_cvt_pk_bf16_f32 v7, v2, v3
	global_store_dwordx4 v[16:17], v[4:7], off offset:256
	s_cbranch_vccz .LBB0_276
	s_waitcnt vmcnt(0)
	s_cmpk_gt_u32 s0, 0xff
	s_cbranch_scc1 .LBB0_287
	s_barrier

; #define PG8_STAGE(bufoff, gbase, voff) do { _Pragma("unroll") for (int _i = 0; _i < 2; ++_i) \
;         __builtin_amdgcn_global_load_lds((const unsigned*)((const char*)(gbase) + (voff)[_i]), (PG8_LAS unsigned*)(lds + (bufoff) + ldsw + _i * 8192), 16, 0, 0); } while (0)
; #define PG8_LDA(dst, b, h) do { _Pragma("unroll") for (int m = 0; m < 4; ++m) _Pragma("unroll") for (int k = 0; k < 2; ++k) dst[m][k] = *(const PG8_LAS bf16x8*)(lds + PG8_SA(b, h) + aoff + m * 2048 + k * 1024); } while (0)
; #define PG8_LDB(dst, b, h) do { _Pragma("unroll") for (int n = 0; n < 2; ++n) _Pragma("unroll") for (int k = 0; k < 2; ++k) dst[n][k] = *(const PG8_LAS bf16x8*)(lds + PG8_SB(b, h) + boff + n * 2048 + k * 1024); } while (0)
; #define PG8_MMA(ai, bj, At, Bt) do { __builtin_amdgcn_s_setprio(1); _Pragma("unroll") for (int m = 0; m < 4; ++m) _Pragma("unroll") for (int n = 0; n < 2; ++n) _Pragma("unroll") for (int k = 0; k < 2; ++k) \
;         acc[ai][bj][m][n] = __builtin_amdgcn_mfma_f32_16x16x32_bf16(Bt[n][k], At[m][k], acc[ai][bj][m][n], 0, 0, 0); __builtin_amdgcn_s_setprio(0); } while (0)
; #define PG8_WAIT_V(n) asm volatile("s_waitcnt vmcnt(" #n ")" ::: "memory")
; #define PG8_WAIT_L(n) asm volatile("s_waitcnt lgkmcnt(" #n ")" ::: "memory")
; template <class Epi, class Sched, bool ALIGN_EPI = false, bool SP2 = false>
; __device__ __forceinline__ void gemm_phase(PG8_LAS unsigned char* lds, const Gemm g, const Sched& S, const Epi& E) {
;     ...
;             const bool last = (t == nt - 2);
;             const char* a1 = cA + (size_t)(t + 1) * kstep;
;             const char* a2 = last ? nA : cA + (size_t)(t + 2) * kstep; const char* b2 = last ? nB : cB + (size_t)(t + 2) * kstep;
;             const char* a3 = a2 + kstep; const char* b3 = b2 + kstep;
;             if (last && has_next) S.a_ready(nxt);
;             if constexpr (SP2) {
;             PG8_LDB(B0, 0, 0); PG8_LDB(B1, 0, 1); PG8_SCHED; PG8_LDA(At, 0, 0); PG8_STAGE(PG8_SA(1, 1), a1 + hstep, voffA);
;             PG8_WAIT_V(8); PG8_WAIT_L(0); PG8_BAR; PG8_MMA(0, 0, At, B0); PG8_MMA(0, 1, At, B1); PG8_BAR; PG8_SCHED;
;             PG8_LDA(At, 0, 1); PG8_STAGE(PG8_SB(0, 0), b2, voffB); PG8_STAGE(PG8_SB(0, 1), b2 + hstep, voffB); PG8_STAGE(PG8_SA(0, 0), a2, voffA);
;             PG8_WAIT_V(8); PG8_WAIT_L(0); PG8_BAR; PG8_MMA(1, 0, At, B0); PG8_MMA(1, 1, At, B1); PG8_BAR; PG8_SCHED;
.LBB0_404:
	ds_read_b128 v[118:121], v217
	ds_read_b128 v[126:129], v217 offset:1024
	ds_read_b128 v[130:133], v217 offset:2048
	ds_read_b128 v[134:137], v217 offset:3072
	ds_read_b128 v[138:141], v218
	ds_read_b128 v[142:145], v218 offset:1024
	ds_read_b128 v[146:149], v218 offset:2048
	ds_read_b128 v[150:153], v218 offset:3072
	s_add_u32 s30, s10, 0xfff80080
	s_addc_u32 s31, s11, -1
	s_cmp_eq_u32 s65, 28
	s_cselect_b32 s75, s1, s31
	s_cselect_b32 s74, s22, s30
	s_cselect_b32 s73, s33, s63
	s_cselect_b32 s72, s46, s47
	s_add_i32 m0, s77, 0xc000
	ds_read_b128 v[154:157], v219
	ds_read_b128 v[166:169], v219 offset:1024
	ds_read_b128 v[170:173], v219 offset:2048
	ds_read_b128 v[174:177], v219 offset:3072
	ds_read_b128 v[204:207], v219 offset:4096
	ds_read_b128 v[208:211], v219 offset:5120
	ds_read_b128 v[226:229], v219 offset:6144
	ds_read_b128 v[230:233], v219 offset:7168
	global_load_lds_dwordx4 v196, s[10:11]
	s_add_i32 m0, s77, 0xe000
	s_nop 0
	global_load_lds_dwordx4 v198, s[10:11]
	s_waitcnt vmcnt(8)
	s_waitcnt lgkmcnt(0)
	s_barrier
	v_mfma_f32_16x16x32_bf16 v[162:165], v[118:121], v[154:157], v[162:165]
	v_mfma_f32_16x16x32_bf16 v[60:63], v[130:133], v[154:157], v[60:63]
	v_mfma_f32_16x16x32_bf16 v[122:125], v[118:121], v[170:173], v[122:125]
	v_mfma_f32_16x16x32_bf16 v[52:55], v[130:133], v[170:173], v[52:55]
	v_mfma_f32_16x16x32_bf16 v[108:111], v[118:121], v[204:207], v[108:111]
	v_mfma_f32_16x16x32_bf16 v[44:47], v[130:133], v[204:207], v[44:47]
	v_mfma_f32_16x16x32_bf16 v[104:107], v[118:121], v[226:229], v[104:107]
	v_mfma_f32_16x16x32_bf16 v[40:43], v[130:133], v[226:229], v[40:43]
	v_mfma_f32_16x16x32_bf16 v[162:165], v[126:129], v[166:169], v[162:165]
	v_mfma_f32_16x16x32_bf16 v[60:63], v[134:137], v[166:169], v[60:63]
	v_mfma_f32_16x16x32_bf16 v[122:125], v[126:129], v[174:177], v[122:125]
	v_mfma_f32_16x16x32_bf16 v[52:55], v[134:137], v[174:177], v[52:55]
	v_mfma_f32_16x16x32_bf16 v[108:111], v[126:129], v[208:211], v[108:111]
	v_mfma_f32_16x16x32_bf16 v[44:47], v[134:137], v[208:211], v[44:47]
	v_mfma_f32_16x16x32_bf16 v[104:107], v[126:129], v[230:233], v[104:107]
	v_mfma_f32_16x16x32_bf16 v[40:43], v[134:137], v[230:233], v[40:43]
	v_mfma_f32_16x16x32_bf16 v[158:161], v[138:141], v[154:157], v[158:161]
	v_mfma_f32_16x16x32_bf16 v[56:59], v[146:149], v[154:157], v[56:59]
	v_mfma_f32_16x16x32_bf16 v[112:115], v[138:141], v[170:173], v[114:117]
	v_mfma_f32_16x16x32_bf16 v[48:51], v[146:149], v[170:173], v[48:51]
	v_mfma_f32_16x16x32_bf16 v[100:103], v[138:141], v[204:207], v[100:103]
	v_mfma_f32_16x16x32_bf16 v[36:39], v[146:149], v[204:207], v[36:39]
	v_mfma_f32_16x16x32_bf16 v[96:99], v[138:141], v[226:229], v[96:99]
	v_mfma_f32_16x16x32_bf16 v[32:35], v[146:149], v[226:229], v[32:35]
	v_mfma_f32_16x16x32_bf16 v[158:161], v[142:145], v[166:169], v[158:161]
	v_mfma_f32_16x16x32_bf16 v[56:59], v[150:153], v[166:169], v[56:59]
	v_mfma_f32_16x16x32_bf16 v[112:115], v[142:145], v[174:177], v[112:115]
	v_mfma_f32_16x16x32_bf16 v[48:51], v[150:153], v[174:177], v[48:51]
	v_mfma_f32_16x16x32_bf16 v[100:103], v[142:145], v[208:211], v[100:103]
	v_mfma_f32_16x16x32_bf16 v[36:39], v[150:153], v[208:211], v[36:39]
	v_mfma_f32_16x16x32_bf16 v[96:99], v[142:145], v[230:233], v[96:99]
	v_mfma_f32_16x16x32_bf16 v[32:35], v[150:153], v[230:233], v[32:35]
	s_barrier
	s_add_i32 s30, s85, s29
	s_mov_b32 m0, s30
	ds_read_b128 v[154:157], v219 offset:16384
	ds_read_b128 v[166:169], v219 offset:17408
	ds_read_b128 v[170:173], v219 offset:18432
	ds_read_b128 v[174:177], v219 offset:19456
	ds_read_b128 v[204:207], v219 offset:20480
	ds_read_b128 v[208:211], v219 offset:21504
	ds_read_b128 v[226:229], v219 offset:22528
	ds_read_b128 v[230:233], v219 offset:23552
	global_load_lds_dwordx4 v184, s[72:73]
	s_add_i32 m0, s30, 0x2000
	s_add_u32 s30, s72, 0x80000
	s_addc_u32 s31, s73, 0
	s_add_i32 s71, s86, s29
	global_load_lds_dwordx4 v180, s[72:73]
	s_mov_b32 m0, s71
	s_nop 0
	global_load_lds_dwordx4 v184, s[30:31]
	s_add_i32 m0, s71, 0x2000
	s_nop 0
	global_load_lds_dwordx4 v180, s[30:31]
	s_mov_b32 m0, s77
	s_nop 0
	global_load_lds_dwordx4 v186, s[74:75]
	s_mov_b32 m0, s78
	s_nop 0
	global_load_lds_dwordx4 v182, s[74:75]
	s_waitcnt vmcnt(8)
	s_waitcnt lgkmcnt(0)
	s_barrier
	v_mfma_f32_16x16x32_bf16 v[92:95], v[118:121], v[154:157], v[92:95]
	v_mfma_f32_16x16x32_bf16 v[28:31], v[130:133], v[154:157], v[28:31]
	v_mfma_f32_16x16x32_bf16 v[84:87], v[118:121], v[170:173], v[84:87]
	v_mfma_f32_16x16x32_bf16 v[20:23], v[130:133], v[170:173], v[20:23]
	v_mfma_f32_16x16x32_bf16 v[76:79], v[118:121], v[204:207], v[76:79]
	v_mfma_f32_16x16x32_bf16 v[12:15], v[130:133], v[204:207], v[12:15]
	v_mfma_f32_16x16x32_bf16 v[72:75], v[118:121], v[226:229], v[72:75]
	v_mfma_f32_16x16x32_bf16 v[8:11], v[130:133], v[226:229], v[8:11]
	v_mfma_f32_16x16x32_bf16 v[92:95], v[126:129], v[166:169], v[92:95]
	v_mfma_f32_16x16x32_bf16 v[28:31], v[134:137], v[166:169], v[28:31]
	v_mfma_f32_16x16x32_bf16 v[84:87], v[126:129], v[174:177], v[84:87]
	v_mfma_f32_16x16x32_bf16 v[20:23], v[134:137], v[174:177], v[20:23]
	v_mfma_f32_16x16x32_bf16 v[76:79], v[126:129], v[208:211], v[76:79]
	v_mfma_f32_16x16x32_bf16 v[12:15], v[134:137], v[208:211], v[12:15]
	v_mfma_f32_16x16x32_bf16 v[72:75], v[126:129], v[230:233], v[72:75]
	v_mfma_f32_16x16x32_bf16 v[8:11], v[134:137], v[230:233], v[8:11]
	v_mfma_f32_16x16x32_bf16 v[88:91], v[138:141], v[154:157], v[88:91]
	v_mfma_f32_16x16x32_bf16 v[24:27], v[146:149], v[154:157], v[24:27]
	v_mfma_f32_16x16x32_bf16 v[80:83], v[138:141], v[170:173], v[80:83]
	v_mfma_f32_16x16x32_bf16 v[16:19], v[146:149], v[170:173], v[16:19]
	v_mfma_f32_16x16x32_bf16 v[68:71], v[138:141], v[204:207], v[68:71]
	v_mfma_f32_16x16x32_bf16 v[4:7], v[146:149], v[204:207], v[4:7]
	v_mfma_f32_16x16x32_bf16 v[64:67], v[138:141], v[226:229], v[64:67]
	v_mfma_f32_16x16x32_bf16 v[0:3], v[146:149], v[226:229], v[0:3]
	v_mfma_f32_16x16x32_bf16 v[88:91], v[142:145], v[166:169], v[88:91]
	v_mfma_f32_16x16x32_bf16 v[24:27], v[150:153], v[166:169], v[24:27]
	v_mfma_f32_16x16x32_bf16 v[80:83], v[142:145], v[174:177], v[80:83]
	v_mfma_f32_16x16x32_bf16 v[16:19], v[150:153], v[174:177], v[16:19]
	v_mfma_f32_16x16x32_bf16 v[68:71], v[142:145], v[208:211], v[68:71]
	v_mfma_f32_16x16x32_bf16 v[4:7], v[150:153], v[208:211], v[4:7]
	v_mfma_f32_16x16x32_bf16 v[64:67], v[142:145], v[230:233], v[64:67]
	v_mfma_f32_16x16x32_bf16 v[0:3], v[150:153], v[230:233], v[0:3]
	s_barrier
; #define PG8_STAGE(bufoff, gbase, voff) do { _Pragma("unroll") for (int _i = 0; _i < 2; ++_i) \
;         __builtin_amdgcn_global_load_lds((const unsigned*)((const char*)(gbase) + (voff)[_i]), (PG8_LAS unsigned*)(lds + (bufoff) + ldsw + _i * 8192), 16, 0, 0); } while (0)
; #define PG8_LDA(dst, b, h) do { _Pragma("unroll") for (int m = 0; m < 4; ++m) _Pragma("unroll") for (int k = 0; k < 2; ++k) dst[m][k] = *(const PG8_LAS bf16x8*)(lds + PG8_SA(b, h) + aoff + m * 2048 + k * 1024); } while (0)
; #define PG8_LDB(dst, b, h) do { _Pragma("unroll") for (int n = 0; n < 2; ++n) _Pragma("unroll") for (int k = 0; k < 2; ++k) dst[n][k] = *(const PG8_LAS bf16x8*)(lds + PG8_SB(b, h) + boff + n * 2048 + k * 1024); } while (0)
; #define PG8_WAIT_V(n) asm volatile("s_waitcnt vmcnt(" #n ")" ::: "memory")
; #define PG8_WAIT_L(n) asm volatile("s_waitcnt lgkmcnt(" #n ")" ::: "memory")
; #define PG8_BAR __builtin_amdgcn_s_barrier()
; #define PG8_SCHED __builtin_amdgcn_sched_barrier(0)
; template <class Epi, class Sched, bool ALIGN_EPI = false, bool SP2 = false>
; __device__ __forceinline__ void gemm_phase(PG8_LAS unsigned char* lds, const Gemm g, const Sched& S, const Epi& E) {
;     ...
;     for (;;) {
;         const bool has_next = S.next(ui + 1, nxt);
;         const char* nA = has_next ? (const char*)g.A + (size_t)nxt.pm * tstep : cA; const char* nB = has_next ? (const char*)g.Bt + (size_t)nxt.pn * tstep : cB;
;         for (int t = 0; t < nt; t += 2) {
;             const bool last = (t == nt - 2);
;             const char* a1 = cA + (size_t)(t + 1) * kstep;
;             const char* a2 = last ? nA : cA + (size_t)(t + 2) * kstep; const char* b2 = last ? nB : cB + (size_t)(t + 2) * kstep;
;             const char* a3 = a2 + kstep; const char* b3 = b2 + kstep;
;             if (last && has_next) S.a_ready(nxt);
;     ...
;             PG8_LDB(B0, 1, 0); PG8_LDB(B1, 1, 1); PG8_SCHED; PG8_LDA(At, 1, 0); PG8_STAGE(PG8_SA(0, 1), a2 + hstep, voffA);
;             PG8_WAIT_V(8); PG8_WAIT_L(0); PG8_BAR; PG8_MMA(0, 0, At, B0); PG8_MMA(0, 1, At, B1); PG8_BAR; PG8_SCHED;
;             PG8_LDA(At, 1, 1); PG8_STAGE(PG8_SB(1, 0), b3, voffB); PG8_STAGE(PG8_SB(1, 1), b3 + hstep, voffB); PG8_STAGE(PG8_SA(1, 0), a3, voffA);
;             PG8_WAIT_V(8); PG8_WAIT_L(0); PG8_BAR; PG8_MMA(1, 0, At, B0); PG8_MMA(1, 1, At, B1); PG8_BAR; PG8_SCHED;
	s_add_i32 s71, 0, 0x18000
	v_add_u32_e32 v116, s71, v213
	s_add_i32 s88, 0, 0x1c000
	ds_read_b128 v[118:121], v116
	ds_read_b128 v[126:129], v116 offset:1024
	ds_read_b128 v[130:133], v116 offset:2048
	ds_read_b128 v[134:137], v116 offset:3072
	v_add_u32_e32 v116, s88, v213
	ds_read_b128 v[138:141], v116
	ds_read_b128 v[142:145], v116 offset:1024
	ds_read_b128 v[146:149], v116 offset:2048
	ds_read_b128 v[150:153], v116 offset:3072
	s_add_u32 s30, s74, 0x80000
	s_addc_u32 s31, s75, 0
	s_mov_b32 m0, s79
	ds_read_b128 v[154:157], v219 offset:32768
	ds_read_b128 v[166:169], v219 offset:33792
	ds_read_b128 v[170:173], v219 offset:34816
	ds_read_b128 v[174:177], v219 offset:35840
	ds_read_b128 v[204:207], v219 offset:36864
	ds_read_b128 v[208:211], v219 offset:37888
	ds_read_b128 v[226:229], v219 offset:38912
	ds_read_b128 v[230:233], v219 offset:39936
	global_load_lds_dwordx4 v186, s[30:31]
	s_mov_b32 m0, s80
	s_nop 0
	global_load_lds_dwordx4 v182, s[30:31]
	s_waitcnt vmcnt(8)
	s_waitcnt lgkmcnt(0)
	s_barrier
	v_mfma_f32_16x16x32_bf16 v[162:165], v[118:121], v[154:157], v[162:165]
	v_mfma_f32_16x16x32_bf16 v[60:63], v[130:133], v[154:157], v[60:63]
	v_mfma_f32_16x16x32_bf16 v[122:125], v[118:121], v[170:173], v[122:125]
	v_mfma_f32_16x16x32_bf16 v[52:55], v[130:133], v[170:173], v[52:55]
	v_mfma_f32_16x16x32_bf16 v[108:111], v[118:121], v[204:207], v[108:111]
	v_mfma_f32_16x16x32_bf16 v[44:47], v[130:133], v[204:207], v[44:47]
	v_mfma_f32_16x16x32_bf16 v[104:107], v[118:121], v[226:229], v[104:107]
	v_mfma_f32_16x16x32_bf16 v[40:43], v[130:133], v[226:229], v[40:43]
	v_mfma_f32_16x16x32_bf16 v[162:165], v[126:129], v[166:169], v[162:165]
	v_mfma_f32_16x16x32_bf16 v[60:63], v[134:137], v[166:169], v[60:63]
	v_mfma_f32_16x16x32_bf16 v[122:125], v[126:129], v[174:177], v[122:125]
	v_mfma_f32_16x16x32_bf16 v[52:55], v[134:137], v[174:177], v[52:55]
	v_mfma_f32_16x16x32_bf16 v[108:111], v[126:129], v[208:211], v[108:111]
	v_mfma_f32_16x16x32_bf16 v[44:47], v[134:137], v[208:211], v[44:47]
	v_mfma_f32_16x16x32_bf16 v[104:107], v[126:129], v[230:233], v[104:107]
	v_mfma_f32_16x16x32_bf16 v[40:43], v[134:137], v[230:233], v[40:43]
	v_mfma_f32_16x16x32_bf16 v[158:161], v[138:141], v[154:157], v[158:161]
	v_mfma_f32_16x16x32_bf16 v[56:59], v[146:149], v[154:157], v[56:59]
	v_mfma_f32_16x16x32_bf16 v[112:115], v[138:141], v[170:173], v[112:115]
	v_mfma_f32_16x16x32_bf16 v[48:51], v[146:149], v[170:173], v[48:51]
	v_mfma_f32_16x16x32_bf16 v[100:103], v[138:141], v[204:207], v[100:103]
	v_mfma_f32_16x16x32_bf16 v[36:39], v[146:149], v[204:207], v[36:39]
	v_mfma_f32_16x16x32_bf16 v[96:99], v[138:141], v[226:229], v[96:99]
	v_mfma_f32_16x16x32_bf16 v[32:35], v[146:149], v[226:229], v[32:35]
	v_mfma_f32_16x16x32_bf16 v[158:161], v[142:145], v[166:169], v[158:161]
	v_mfma_f32_16x16x32_bf16 v[56:59], v[150:153], v[166:169], v[56:59]
	v_mfma_f32_16x16x32_bf16 v[114:117], v[142:145], v[174:177], v[112:115]
	v_mfma_f32_16x16x32_bf16 v[48:51], v[150:153], v[174:177], v[48:51]
	v_mfma_f32_16x16x32_bf16 v[100:103], v[142:145], v[208:211], v[100:103]
	v_mfma_f32_16x16x32_bf16 v[36:39], v[150:153], v[208:211], v[36:39]
	v_mfma_f32_16x16x32_bf16 v[96:99], v[142:145], v[230:233], v[96:99]
	v_mfma_f32_16x16x32_bf16 v[32:35], v[150:153], v[230:233], v[32:35]
	s_barrier
	s_add_i32 s30, s71, s29
	s_mov_b32 m0, s30
	ds_read_b128 v[154:157], v219 offset:49152
	ds_read_b128 v[166:169], v219 offset:50176
	ds_read_b128 v[170:173], v219 offset:51200
	ds_read_b128 v[174:177], v219 offset:52224
	ds_read_b128 v[204:207], v219 offset:53248
	ds_read_b128 v[208:211], v219 offset:54272
	ds_read_b128 v[226:229], v219 offset:55296
	ds_read_b128 v[230:233], v219 offset:56320
	s_add_u32 s52, s72, 0x80
	s_addc_u32 s53, s73, 0
	global_load_lds_dwordx4 v184, s[52:53]
	s_add_i32 m0, s30, 0x2000
	s_add_u32 s30, s72, 0x80080
	s_addc_u32 s31, s73, 0
	s_add_i32 s71, s88, s29
	global_load_lds_dwordx4 v180, s[52:53]
	s_mov_b32 m0, s71
	s_nop 0
	global_load_lds_dwordx4 v184, s[30:31]
	s_add_i32 m0, s71, 0x2000
	s_nop 0
	global_load_lds_dwordx4 v180, s[30:31]
	s_mov_b32 m0, s83
	s_nop 0
	s_add_u32 s52, s74, 0x80
	s_addc_u32 s53, s75, 0
	global_load_lds_dwordx4 v186, s[52:53]
	s_mov_b32 m0, s84
	s_nop 0
	global_load_lds_dwordx4 v182, s[52:53]
	s_waitcnt vmcnt(8)
	s_waitcnt lgkmcnt(0)
	s_barrier
	v_mfma_f32_16x16x32_bf16 v[92:95], v[118:121], v[154:157], v[92:95]
	v_mfma_f32_16x16x32_bf16 v[28:31], v[130:133], v[154:157], v[28:31]
	v_mfma_f32_16x16x32_bf16 v[84:87], v[118:121], v[170:173], v[84:87]
	v_mfma_f32_16x16x32_bf16 v[20:23], v[130:133], v[170:173], v[20:23]
	v_mfma_f32_16x16x32_bf16 v[76:79], v[118:121], v[204:207], v[76:79]
	v_mfma_f32_16x16x32_bf16 v[12:15], v[130:133], v[204:207], v[12:15]
	v_mfma_f32_16x16x32_bf16 v[72:75], v[118:121], v[226:229], v[72:75]
	v_mfma_f32_16x16x32_bf16 v[8:11], v[130:133], v[226:229], v[8:11]
	v_mfma_f32_16x16x32_bf16 v[92:95], v[126:129], v[166:169], v[92:95]
	v_mfma_f32_16x16x32_bf16 v[28:31], v[134:137], v[166:169], v[28:31]
	v_mfma_f32_16x16x32_bf16 v[84:87], v[126:129], v[174:177], v[84:87]
	v_mfma_f32_16x16x32_bf16 v[20:23], v[134:137], v[174:177], v[20:23]
	v_mfma_f32_16x16x32_bf16 v[76:79], v[126:129], v[208:211], v[76:79]
	v_mfma_f32_16x16x32_bf16 v[12:15], v[134:137], v[208:211], v[12:15]
	v_mfma_f32_16x16x32_bf16 v[72:75], v[126:129], v[230:233], v[72:75]
	v_mfma_f32_16x16x32_bf16 v[8:11], v[134:137], v[230:233], v[8:11]
	v_mfma_f32_16x16x32_bf16 v[88:91], v[138:141], v[154:157], v[88:91]
	v_mfma_f32_16x16x32_bf16 v[24:27], v[146:149], v[154:157], v[24:27]
	v_mfma_f32_16x16x32_bf16 v[80:83], v[138:141], v[170:173], v[80:83]
	v_mfma_f32_16x16x32_bf16 v[16:19], v[146:149], v[170:173], v[16:19]
	v_mfma_f32_16x16x32_bf16 v[68:71], v[138:141], v[204:207], v[68:71]
	v_mfma_f32_16x16x32_bf16 v[4:7], v[146:149], v[204:207], v[4:7]
	v_mfma_f32_16x16x32_bf16 v[64:67], v[138:141], v[226:229], v[64:67]
	v_mfma_f32_16x16x32_bf16 v[0:3], v[146:149], v[226:229], v[0:3]
	v_mfma_f32_16x16x32_bf16 v[88:91], v[142:145], v[166:169], v[88:91]
	v_mfma_f32_16x16x32_bf16 v[24:27], v[150:153], v[166:169], v[24:27]
	v_mfma_f32_16x16x32_bf16 v[80:83], v[142:145], v[174:177], v[80:83]
	v_mfma_f32_16x16x32_bf16 v[16:19], v[150:153], v[174:177], v[16:19]
	v_mfma_f32_16x16x32_bf16 v[68:71], v[142:145], v[208:211], v[68:71]
	v_mfma_f32_16x16x32_bf16 v[4:7], v[150:153], v[208:211], v[4:7]
	v_mfma_f32_16x16x32_bf16 v[64:67], v[142:145], v[230:233], v[64:67]
	v_mfma_f32_16x16x32_bf16 v[0:3], v[150:153], v[230:233], v[0:3]
	s_barrier
	s_add_i32 s65, s65, 2
	s_add_u32 s10, s10, 0x100
	s_addc_u32 s11, s11, 0
	s_add_u32 s47, s47, 0x100
	s_addc_u32 s63, s63, 0
	s_cmp_gt_u32 s65, 29
	s_cbranch_scc0 .LBB0_404
	s_and_b64 vcc, exec, s[54:55]
	s_cbranch_vccz .LBB0_407
	s_barrier

; #define PG8_STAGE(bufoff, gbase, voff) do { _Pragma("unroll") for (int _i = 0; _i < 2; ++_i) \
;         __builtin_amdgcn_global_load_lds((const unsigned*)((const char*)(gbase) + (voff)[_i]), (PG8_LAS unsigned*)(lds + (bufoff) + ldsw + _i * 8192), 16, 0, 0); } while (0)
; #define PG8_LDA(dst, b, h) do { _Pragma("unroll") for (int m = 0; m < 4; ++m) _Pragma("unroll") for (int k = 0; k < 2; ++k) dst[m][k] = *(const PG8_LAS bf16x8*)(lds + PG8_SA(b, h) + aoff + m * 2048 + k * 1024); } while (0)
; #define PG8_LDB(dst, b, h) do { _Pragma("unroll") for (int n = 0; n < 2; ++n) _Pragma("unroll") for (int k = 0; k < 2; ++k) dst[n][k] = *(const PG8_LAS bf16x8*)(lds + PG8_SB(b, h) + boff + n * 2048 + k * 1024); } while (0)
; #define PG8_MMA(ai, bj, At, Bt) do { __builtin_amdgcn_s_setprio(1); _Pragma("unroll") for (int m = 0; m < 4; ++m) _Pragma("unroll") for (int n = 0; n < 2; ++n) _Pragma("unroll") for (int k = 0; k < 2; ++k) \
;         acc[ai][bj][m][n] = __builtin_amdgcn_mfma_f32_16x16x32_bf16(Bt[n][k], At[m][k], acc[ai][bj][m][n], 0, 0, 0); __builtin_amdgcn_s_setprio(0); } while (0)
; #define PG8_WAIT_V(n) asm volatile("s_waitcnt vmcnt(" #n ")" ::: "memory")
; #define PG8_BAR __builtin_amdgcn_s_barrier()
; template <class Epi, class Sched, bool ALIGN_EPI = false, bool SP2 = false>
; __device__ __forceinline__ void gemm_phase(PG8_LAS unsigned char* lds, const Gemm g, const Sched& S, const Epi& E) {
;     ...
;         for (int t = 0; t < nt; t += 2) {
;             const bool last = (t == nt - 2);
;             const char* a1 = cA + (size_t)(t + 1) * kstep;
;             const char* a2 = last ? nA : cA + (size_t)(t + 2) * kstep; const char* b2 = last ? nB : cB + (size_t)(t + 2) * kstep;
;             const char* a3 = a2 + kstep; const char* b3 = b2 + kstep;
;             if (last && has_next) S.a_ready(nxt);
;             if constexpr (SP2) {
;             PG8_LDB(B0, 0, 0); PG8_LDB(B1, 0, 1); PG8_SCHED; PG8_LDA(At, 0, 0); PG8_STAGE(PG8_SA(1, 1), a1 + hstep, voffA);
;             PG8_WAIT_V(8); PG8_WAIT_L(0); PG8_BAR; PG8_MMA(0, 0, At, B0); PG8_MMA(0, 1, At, B1); PG8_BAR; PG8_SCHED;
;             PG8_LDA(At, 0, 1); PG8_STAGE(PG8_SB(0, 0), b2, voffB); PG8_STAGE(PG8_SB(0, 1), b2 + hstep, voffB); PG8_STAGE(PG8_SA(0, 0), a2, voffA);
;             PG8_WAIT_V(8); PG8_WAIT_L(0); PG8_BAR; PG8_MMA(1, 0, At, B0); PG8_MMA(1, 1, At, B1); PG8_BAR; PG8_SCHED;
.LBB0_552:
	ds_read_b128 v[152:155], v149
	ds_read_b128 v[156:159], v149 offset:1024
	ds_read_b128 v[160:163], v149 offset:2048
	ds_read_b128 v[164:167], v149 offset:3072
	ds_read_b128 v[168:171], v150
	ds_read_b128 v[172:175], v150 offset:1024
	ds_read_b128 v[180:183], v150 offset:2048
	ds_read_b128 v[184:187], v150 offset:3072
	s_add_u32 s34, s26, 0x100
	s_addc_u32 s35, s27, 0
	s_cmpk_eq_i32 s67, 0x54
	s_cselect_b32 s45, s7, s35
	s_cselect_b32 s44, s6, s34
	s_cselect_b32 s37, s9, s66
	s_cselect_b32 s36, s8, s65
	s_add_i32 m0, s29, 0xc000
	ds_read_b128 v[188:191], v151
	ds_read_b128 v[192:195], v151 offset:1024
	ds_read_b128 v[196:199], v151 offset:2048
	ds_read_b128 v[200:203], v151 offset:3072
	ds_read_b128 v[204:207], v151 offset:4096
	ds_read_b128 v[208:211], v151 offset:5120
	ds_read_b128 v[212:215], v151 offset:6144
	ds_read_b128 v[216:219], v151 offset:7168
	global_load_lds_dwordx4 v136, s[26:27]
	s_add_i32 m0, s29, 0xe000
	s_nop 0
	global_load_lds_dwordx4 v138, s[26:27]
	s_waitcnt vmcnt(8)
	s_waitcnt lgkmcnt(0)
	s_barrier
	v_mfma_f32_16x16x32_bf16 v[124:127], v[152:155], v[188:191], v[124:127]
	v_mfma_f32_16x16x32_bf16 v[120:123], v[160:163], v[188:191], v[120:123]
	v_mfma_f32_16x16x32_bf16 v[116:119], v[152:155], v[196:199], v[116:119]
	v_mfma_f32_16x16x32_bf16 v[108:111], v[160:163], v[196:199], v[108:111]
	v_mfma_f32_16x16x32_bf16 v[100:103], v[152:155], v[204:207], v[100:103]
	v_mfma_f32_16x16x32_bf16 v[92:95], v[160:163], v[204:207], v[92:95]
	v_mfma_f32_16x16x32_bf16 v[84:87], v[152:155], v[212:215], v[84:87]
	v_mfma_f32_16x16x32_bf16 v[76:79], v[160:163], v[212:215], v[76:79]
	v_mfma_f32_16x16x32_bf16 v[124:127], v[156:159], v[192:195], v[124:127]
	v_mfma_f32_16x16x32_bf16 v[120:123], v[164:167], v[192:195], v[120:123]
	v_mfma_f32_16x16x32_bf16 v[116:119], v[156:159], v[200:203], v[116:119]
	v_mfma_f32_16x16x32_bf16 v[108:111], v[164:167], v[200:203], v[108:111]
	v_mfma_f32_16x16x32_bf16 v[100:103], v[156:159], v[208:211], v[100:103]
	v_mfma_f32_16x16x32_bf16 v[92:95], v[164:167], v[208:211], v[92:95]
	v_mfma_f32_16x16x32_bf16 v[84:87], v[156:159], v[216:219], v[84:87]
	v_mfma_f32_16x16x32_bf16 v[76:79], v[164:167], v[216:219], v[76:79]
	v_mfma_f32_16x16x32_bf16 v[112:115], v[168:171], v[188:191], v[112:115]
	v_mfma_f32_16x16x32_bf16 v[104:107], v[180:183], v[188:191], v[104:107]
	v_mfma_f32_16x16x32_bf16 v[96:99], v[168:171], v[196:199], v[96:99]
	v_mfma_f32_16x16x32_bf16 v[88:91], v[180:183], v[196:199], v[88:91]
	v_mfma_f32_16x16x32_bf16 v[80:83], v[168:171], v[204:207], v[80:83]
	v_mfma_f32_16x16x32_bf16 v[72:75], v[180:183], v[204:207], v[72:75]
	v_mfma_f32_16x16x32_bf16 v[68:71], v[168:171], v[212:215], v[68:71]
	v_mfma_f32_16x16x32_bf16 v[64:67], v[180:183], v[212:215], v[64:67]
	v_mfma_f32_16x16x32_bf16 v[112:115], v[172:175], v[192:195], v[112:115]
	v_mfma_f32_16x16x32_bf16 v[104:107], v[184:187], v[192:195], v[104:107]
	v_mfma_f32_16x16x32_bf16 v[96:99], v[172:175], v[200:203], v[96:99]
	v_mfma_f32_16x16x32_bf16 v[88:91], v[184:187], v[200:203], v[88:91]
	v_mfma_f32_16x16x32_bf16 v[80:83], v[172:175], v[208:211], v[80:83]
	v_mfma_f32_16x16x32_bf16 v[72:75], v[184:187], v[208:211], v[72:75]
	v_mfma_f32_16x16x32_bf16 v[68:71], v[172:175], v[216:219], v[68:71]
	v_mfma_f32_16x16x32_bf16 v[64:67], v[184:187], v[216:219], v[64:67]
	s_barrier
	s_add_i32 s26, s55, s1
	s_mov_b32 m0, s26
	ds_read_b128 v[188:191], v151 offset:16384
	ds_read_b128 v[192:195], v151 offset:17408
	ds_read_b128 v[196:199], v151 offset:18432
	ds_read_b128 v[200:203], v151 offset:19456
	ds_read_b128 v[204:207], v151 offset:20480
	ds_read_b128 v[208:211], v151 offset:21504
	ds_read_b128 v[212:215], v151 offset:22528
	ds_read_b128 v[216:219], v151 offset:23552
	global_load_lds_dwordx4 v130, s[36:37]
	s_add_i32 m0, s26, 0x2000
	s_add_u32 s26, s36, 0x160000
	s_addc_u32 s27, s37, 0
	s_add_i32 s30, s56, s1
	global_load_lds_dwordx4 v134, s[36:37]
	s_mov_b32 m0, s30
	s_nop 0
	global_load_lds_dwordx4 v130, s[26:27]
	s_add_i32 m0, s30, 0x2000
	s_nop 0
	global_load_lds_dwordx4 v134, s[26:27]
	s_mov_b32 m0, s29
	s_nop 0
	global_load_lds_dwordx4 v128, s[44:45]
	s_mov_b32 m0, s33
	s_nop 0
	global_load_lds_dwordx4 v132, s[44:45]
	s_waitcnt vmcnt(8)
	s_waitcnt lgkmcnt(0)
	s_barrier
	v_mfma_f32_16x16x32_bf16 v[60:63], v[152:155], v[188:191], v[60:63]
	v_mfma_f32_16x16x32_bf16 v[56:59], v[160:163], v[188:191], v[56:59]
	v_mfma_f32_16x16x32_bf16 v[52:55], v[152:155], v[196:199], v[52:55]
	v_mfma_f32_16x16x32_bf16 v[44:47], v[160:163], v[196:199], v[44:47]
	v_mfma_f32_16x16x32_bf16 v[36:39], v[152:155], v[204:207], v[36:39]
	v_mfma_f32_16x16x32_bf16 v[28:31], v[160:163], v[204:207], v[28:31]
	v_mfma_f32_16x16x32_bf16 v[20:23], v[152:155], v[212:215], v[20:23]
	v_mfma_f32_16x16x32_bf16 v[12:15], v[160:163], v[212:215], v[12:15]
	v_mfma_f32_16x16x32_bf16 v[60:63], v[156:159], v[192:195], v[60:63]
	v_mfma_f32_16x16x32_bf16 v[56:59], v[164:167], v[192:195], v[56:59]
	v_mfma_f32_16x16x32_bf16 v[52:55], v[156:159], v[200:203], v[52:55]
	v_mfma_f32_16x16x32_bf16 v[44:47], v[164:167], v[200:203], v[44:47]
	v_mfma_f32_16x16x32_bf16 v[36:39], v[156:159], v[208:211], v[36:39]
	v_mfma_f32_16x16x32_bf16 v[28:31], v[164:167], v[208:211], v[28:31]
	v_mfma_f32_16x16x32_bf16 v[20:23], v[156:159], v[216:219], v[20:23]
	v_mfma_f32_16x16x32_bf16 v[12:15], v[164:167], v[216:219], v[12:15]
	v_mfma_f32_16x16x32_bf16 v[48:51], v[168:171], v[188:191], v[48:51]
	v_mfma_f32_16x16x32_bf16 v[40:43], v[180:183], v[188:191], v[40:43]
	v_mfma_f32_16x16x32_bf16 v[32:35], v[168:171], v[196:199], v[32:35]
	v_mfma_f32_16x16x32_bf16 v[24:27], v[180:183], v[196:199], v[24:27]
	v_mfma_f32_16x16x32_bf16 v[16:19], v[168:171], v[204:207], v[16:19]
	v_mfma_f32_16x16x32_bf16 v[8:11], v[180:183], v[204:207], v[8:11]
	v_mfma_f32_16x16x32_bf16 v[4:7], v[168:171], v[212:215], v[4:7]
	v_mfma_f32_16x16x32_bf16 v[0:3], v[180:183], v[212:215], v[0:3]
	v_mfma_f32_16x16x32_bf16 v[48:51], v[172:175], v[192:195], v[48:51]
	v_mfma_f32_16x16x32_bf16 v[40:43], v[184:187], v[192:195], v[40:43]
	v_mfma_f32_16x16x32_bf16 v[32:35], v[172:175], v[200:203], v[32:35]
	v_mfma_f32_16x16x32_bf16 v[24:27], v[184:187], v[200:203], v[24:27]
	v_mfma_f32_16x16x32_bf16 v[16:19], v[172:175], v[208:211], v[16:19]
	v_mfma_f32_16x16x32_bf16 v[8:11], v[184:187], v[208:211], v[8:11]
	v_mfma_f32_16x16x32_bf16 v[4:7], v[172:175], v[216:219], v[4:7]
	v_mfma_f32_16x16x32_bf16 v[0:3], v[184:187], v[216:219], v[0:3]
	s_barrier
; #define PG8_STAGE(bufoff, gbase, voff) do { _Pragma("unroll") for (int _i = 0; _i < 2; ++_i) \
;         __builtin_amdgcn_global_load_lds((const unsigned*)((const char*)(gbase) + (voff)[_i]), (PG8_LAS unsigned*)(lds + (bufoff) + ldsw + _i * 8192), 16, 0, 0); } while (0)
; #define PG8_LDA(dst, b, h) do { _Pragma("unroll") for (int m = 0; m < 4; ++m) _Pragma("unroll") for (int k = 0; k < 2; ++k) dst[m][k] = *(const PG8_LAS bf16x8*)(lds + PG8_SA(b, h) + aoff + m * 2048 + k * 1024); } while (0)
; #define PG8_LDB(dst, b, h) do { _Pragma("unroll") for (int n = 0; n < 2; ++n) _Pragma("unroll") for (int k = 0; k < 2; ++k) dst[n][k] = *(const PG8_LAS bf16x8*)(lds + PG8_SB(b, h) + boff + n * 2048 + k * 1024); } while (0)
; #define PG8_MMA(ai, bj, At, Bt) do { __builtin_amdgcn_s_setprio(1); _Pragma("unroll") for (int m = 0; m < 4; ++m) _Pragma("unroll") for (int n = 0; n < 2; ++n) _Pragma("unroll") for (int k = 0; k < 2; ++k) \
;         acc[ai][bj][m][n] = __builtin_amdgcn_mfma_f32_16x16x32_bf16(Bt[n][k], At[m][k], acc[ai][bj][m][n], 0, 0, 0); __builtin_amdgcn_s_setprio(0); } while (0)
; #define PG8_WAIT_V(n) asm volatile("s_waitcnt vmcnt(" #n ")" ::: "memory")
; #define PG8_WAIT_L(n) asm volatile("s_waitcnt lgkmcnt(" #n ")" ::: "memory")
; #define PG8_BAR __builtin_amdgcn_s_barrier()
; #define PG8_SCHED __builtin_amdgcn_sched_barrier(0)
; template <class Epi, class Sched, bool ALIGN_EPI = false, bool SP2 = false>
; __device__ __forceinline__ void gemm_phase(PG8_LAS unsigned char* lds, const Gemm g, const Sched& S, const Epi& E) {
;     ...
;             PG8_LDB(B0, 1, 0); PG8_LDB(B1, 1, 1); PG8_SCHED; PG8_LDA(At, 1, 0); PG8_STAGE(PG8_SA(0, 1), a2 + hstep, voffA);
;             PG8_WAIT_V(8); PG8_WAIT_L(0); PG8_BAR; PG8_MMA(0, 0, At, B0); PG8_MMA(0, 1, At, B1); PG8_BAR; PG8_SCHED;
;             PG8_LDA(At, 1, 1); PG8_STAGE(PG8_SB(1, 0), b3, voffB); PG8_STAGE(PG8_SB(1, 1), b3 + hstep, voffB); PG8_STAGE(PG8_SA(1, 0), a3, voffA);
;             PG8_WAIT_V(8); PG8_WAIT_L(0); PG8_BAR; PG8_MMA(1, 0, At, B0); PG8_MMA(1, 1, At, B1); PG8_BAR; PG8_SCHED;
	s_add_i32 s30, 0, 0x18000
	s_add_i32 s31, 0, 0x1c000
	v_add_u32_e32 v164, s30, v147
	v_add_u32_e32 v184, s31, v147
	ds_read_b128 v[152:155], v164
	ds_read_b128 v[156:159], v164 offset:1024
	ds_read_b128 v[160:163], v164 offset:2048
	ds_read_b128 v[164:167], v164 offset:3072
	ds_read_b128 v[168:171], v184
	ds_read_b128 v[172:175], v184 offset:1024
	ds_read_b128 v[180:183], v184 offset:2048
	ds_read_b128 v[184:187], v184 offset:3072
	s_add_u32 s26, s44, 0x160000
	s_addc_u32 s27, s45, 0
	s_mov_b32 m0, s46
	ds_read_b128 v[188:191], v151 offset:32768
	ds_read_b128 v[192:195], v151 offset:33792
	ds_read_b128 v[196:199], v151 offset:34816
	ds_read_b128 v[200:203], v151 offset:35840
	ds_read_b128 v[204:207], v151 offset:36864
	ds_read_b128 v[208:211], v151 offset:37888
	ds_read_b128 v[212:215], v151 offset:38912
	ds_read_b128 v[216:219], v151 offset:39936
	global_load_lds_dwordx4 v128, s[26:27]
	s_mov_b32 m0, s47
	s_nop 0
	global_load_lds_dwordx4 v132, s[26:27]
	s_waitcnt vmcnt(8)
	s_waitcnt lgkmcnt(0)
	s_barrier
	v_mfma_f32_16x16x32_bf16 v[124:127], v[152:155], v[188:191], v[124:127]
	v_mfma_f32_16x16x32_bf16 v[120:123], v[160:163], v[188:191], v[120:123]
	v_mfma_f32_16x16x32_bf16 v[116:119], v[152:155], v[196:199], v[116:119]
	v_mfma_f32_16x16x32_bf16 v[108:111], v[160:163], v[196:199], v[108:111]
	v_mfma_f32_16x16x32_bf16 v[100:103], v[152:155], v[204:207], v[100:103]
	v_mfma_f32_16x16x32_bf16 v[92:95], v[160:163], v[204:207], v[92:95]
	v_mfma_f32_16x16x32_bf16 v[84:87], v[152:155], v[212:215], v[84:87]
	v_mfma_f32_16x16x32_bf16 v[76:79], v[160:163], v[212:215], v[76:79]
	v_mfma_f32_16x16x32_bf16 v[124:127], v[156:159], v[192:195], v[124:127]
	v_mfma_f32_16x16x32_bf16 v[120:123], v[164:167], v[192:195], v[120:123]
	v_mfma_f32_16x16x32_bf16 v[116:119], v[156:159], v[200:203], v[116:119]
	v_mfma_f32_16x16x32_bf16 v[108:111], v[164:167], v[200:203], v[108:111]
	v_mfma_f32_16x16x32_bf16 v[100:103], v[156:159], v[208:211], v[100:103]
	v_mfma_f32_16x16x32_bf16 v[92:95], v[164:167], v[208:211], v[92:95]
	v_mfma_f32_16x16x32_bf16 v[84:87], v[156:159], v[216:219], v[84:87]
	v_mfma_f32_16x16x32_bf16 v[76:79], v[164:167], v[216:219], v[76:79]
	v_mfma_f32_16x16x32_bf16 v[112:115], v[168:171], v[188:191], v[112:115]
	v_mfma_f32_16x16x32_bf16 v[104:107], v[180:183], v[188:191], v[104:107]
	v_mfma_f32_16x16x32_bf16 v[96:99], v[168:171], v[196:199], v[96:99]
	v_mfma_f32_16x16x32_bf16 v[88:91], v[180:183], v[196:199], v[88:91]
	v_mfma_f32_16x16x32_bf16 v[80:83], v[168:171], v[204:207], v[80:83]
	v_mfma_f32_16x16x32_bf16 v[72:75], v[180:183], v[204:207], v[72:75]
	v_mfma_f32_16x16x32_bf16 v[68:71], v[168:171], v[212:215], v[68:71]
	v_mfma_f32_16x16x32_bf16 v[64:67], v[180:183], v[212:215], v[64:67]
	v_mfma_f32_16x16x32_bf16 v[112:115], v[172:175], v[192:195], v[112:115]
	v_mfma_f32_16x16x32_bf16 v[104:107], v[184:187], v[192:195], v[104:107]
	v_mfma_f32_16x16x32_bf16 v[96:99], v[172:175], v[200:203], v[96:99]
	v_mfma_f32_16x16x32_bf16 v[88:91], v[184:187], v[200:203], v[88:91]
	v_mfma_f32_16x16x32_bf16 v[80:83], v[172:175], v[208:211], v[80:83]
	v_mfma_f32_16x16x32_bf16 v[72:75], v[184:187], v[208:211], v[72:75]
	v_mfma_f32_16x16x32_bf16 v[68:71], v[172:175], v[216:219], v[68:71]
	v_mfma_f32_16x16x32_bf16 v[64:67], v[184:187], v[216:219], v[64:67]
	s_barrier
	s_add_i32 s26, s30, s1
	s_mov_b32 m0, s26
	ds_read_b128 v[188:191], v151 offset:49152
	ds_read_b128 v[192:195], v151 offset:50176
	ds_read_b128 v[196:199], v151 offset:51200
	ds_read_b128 v[200:203], v151 offset:52224
	ds_read_b128 v[204:207], v151 offset:53248
	ds_read_b128 v[208:211], v151 offset:54272
	ds_read_b128 v[212:215], v151 offset:55296
	ds_read_b128 v[216:219], v151 offset:56320
	s_add_u32 s10, s36, 0x80
	s_addc_u32 s11, s37, 0
	global_load_lds_dwordx4 v130, s[10:11]
	s_add_i32 m0, s26, 0x2000
	s_add_u32 s26, s36, 0x160080
	s_addc_u32 s27, s37, 0
	s_add_i32 s30, s31, s1
	global_load_lds_dwordx4 v134, s[10:11]
	s_mov_b32 m0, s30
	s_nop 0
	global_load_lds_dwordx4 v130, s[26:27]
	s_add_i32 m0, s30, 0x2000
	s_nop 0
	global_load_lds_dwordx4 v134, s[26:27]
	s_mov_b32 m0, s53
	s_nop 0
	s_add_u32 s10, s44, 0x80
	s_addc_u32 s11, s45, 0
	global_load_lds_dwordx4 v128, s[10:11]
	s_mov_b32 m0, s54
	s_nop 0
	global_load_lds_dwordx4 v132, s[10:11]
	s_waitcnt vmcnt(8)
	s_waitcnt lgkmcnt(0)
	s_barrier
	v_mfma_f32_16x16x32_bf16 v[60:63], v[152:155], v[188:191], v[60:63]
	v_mfma_f32_16x16x32_bf16 v[56:59], v[160:163], v[188:191], v[56:59]
	v_mfma_f32_16x16x32_bf16 v[52:55], v[152:155], v[196:199], v[52:55]
	v_mfma_f32_16x16x32_bf16 v[44:47], v[160:163], v[196:199], v[44:47]
	v_mfma_f32_16x16x32_bf16 v[36:39], v[152:155], v[204:207], v[36:39]
	v_mfma_f32_16x16x32_bf16 v[28:31], v[160:163], v[204:207], v[28:31]
	v_mfma_f32_16x16x32_bf16 v[20:23], v[152:155], v[212:215], v[20:23]
	v_mfma_f32_16x16x32_bf16 v[12:15], v[160:163], v[212:215], v[12:15]
	v_mfma_f32_16x16x32_bf16 v[60:63], v[156:159], v[192:195], v[60:63]
	v_mfma_f32_16x16x32_bf16 v[56:59], v[164:167], v[192:195], v[56:59]
	v_mfma_f32_16x16x32_bf16 v[52:55], v[156:159], v[200:203], v[52:55]
	v_mfma_f32_16x16x32_bf16 v[44:47], v[164:167], v[200:203], v[44:47]
	v_mfma_f32_16x16x32_bf16 v[36:39], v[156:159], v[208:211], v[36:39]
	v_mfma_f32_16x16x32_bf16 v[28:31], v[164:167], v[208:211], v[28:31]
	v_mfma_f32_16x16x32_bf16 v[20:23], v[156:159], v[216:219], v[20:23]
	v_mfma_f32_16x16x32_bf16 v[12:15], v[164:167], v[216:219], v[12:15]
	v_mfma_f32_16x16x32_bf16 v[48:51], v[168:171], v[188:191], v[48:51]
	v_mfma_f32_16x16x32_bf16 v[40:43], v[180:183], v[188:191], v[40:43]
	v_mfma_f32_16x16x32_bf16 v[32:35], v[168:171], v[196:199], v[32:35]
	v_mfma_f32_16x16x32_bf16 v[24:27], v[180:183], v[196:199], v[24:27]
	v_mfma_f32_16x16x32_bf16 v[16:19], v[168:171], v[204:207], v[16:19]
	v_mfma_f32_16x16x32_bf16 v[8:11], v[180:183], v[204:207], v[8:11]
	v_mfma_f32_16x16x32_bf16 v[4:7], v[168:171], v[212:215], v[4:7]
	v_mfma_f32_16x16x32_bf16 v[0:3], v[180:183], v[212:215], v[0:3]
	v_mfma_f32_16x16x32_bf16 v[48:51], v[172:175], v[192:195], v[48:51]
	v_mfma_f32_16x16x32_bf16 v[40:43], v[184:187], v[192:195], v[40:43]
	v_mfma_f32_16x16x32_bf16 v[32:35], v[172:175], v[200:203], v[32:35]
	v_mfma_f32_16x16x32_bf16 v[24:27], v[184:187], v[200:203], v[24:27]
	v_mfma_f32_16x16x32_bf16 v[16:19], v[172:175], v[208:211], v[16:19]
	v_mfma_f32_16x16x32_bf16 v[8:11], v[184:187], v[208:211], v[8:11]
	v_mfma_f32_16x16x32_bf16 v[4:7], v[172:175], v[216:219], v[4:7]
	v_mfma_f32_16x16x32_bf16 v[0:3], v[184:187], v[216:219], v[0:3]
	s_barrier
; __device__ __forceinline__ unsigned cvt_pk_bf16(float lo, float hi) { unsigned r; asm volatile("v_cvt_pk_bf16_f32 %0, %1, %2" : "=v"(r) : "v"(lo), "v"(hi)); return r; }
; #define PG8_WAIT_V(n) asm volatile("s_waitcnt vmcnt(" #n ")" ::: "memory")
; #define PG8_BAR __builtin_amdgcn_s_barrier()
;     __device__ __forceinline__ void operator()(const f32x4 (&acc)[2][2][4][2], const Unit& u, int wr, int wc, int fr, int fq) const {
;         const int row0 = u.pm * BM + wr * 64 + fr; const int col0 = u.pn * BM + wc * 32 + 8 * fq;
; #pragma unroll
;         for (int ai = 0; ai < 2; ++ai)
; #pragma unroll
;             for (int m = 0; m < 4; ++m) { bf16_t* rowp = O + (size_t)(row0 + ai * HALF + m * 16) * ldc + col0;
; #pragma unroll
;                 for (int bj = 0; bj < 2; ++bj) { const f32x4 v0 = acc[ai][bj][m][0], v1 = acc[ai][bj][m][1];
;                     u32x4 w; w.x = cvt_pk_bf16(v0[0], v0[1]); w.y = cvt_pk_bf16(v0[2], v0[3]); w.z = cvt_pk_bf16(v1[0], v1[1]); w.w = cvt_pk_bf16(v1[2], v1[3]);
;                     *(u32x4*)(rowp + bj * HALF) = w; } }
; template <class Epi, class Sched, bool ALIGN_EPI = false, bool SP2 = false>
; __device__ __forceinline__ void gemm_phase(PG8_LAS unsigned char* lds, const Gemm g, const Sched& S, const Epi& E) {
;     ...
;         if constexpr (!Epi::AFTER_DRAIN) { E(acc, cur, wr, wc, fr, fq); S.done(cur); }
;         if (!has_next) break;
; #pragma unroll
;         for (int a = 0; a < 2; ++a)
; #pragma unroll
;             for (int b = 0; b < 2; ++b)
; #pragma unroll
;                 for (int m = 0; m < 4; ++m)
; #pragma unroll
;                     for (int n = 0; n < 2; ++n) acc[a][b][m][n] = (f32x4){0.f, 0.f, 0.f, 0.f};
;         cur = nxt; cA = nA; cB = nB; ++ui;
;         if constexpr (ALIGN_EPI) { if (wr == 1) PG8_BAR; }
;     }
;     PG8_WAIT_V(0);
;     if constexpr (!ALIGN_EPI) { if (wr == 0) PG8_BAR; }
	s_add_i32 s67, s67, 2
	s_add_u32 s65, s65, 0x100
	s_addc_u32 s66, s66, 0
	s_cmpk_gt_u32 s67, 0x55
	s_mov_b64 s[26:27], s[34:35]
	s_cbranch_scc0 .LBB0_552
	v_lshl_add_u32 v152, s63, 8, v146
	v_lshl_or_b32 v144, s64, 8, v148
	v_ashrrev_i32_e32 v153, 31, v152
	v_ashrrev_i32_e32 v145, 31, v144
	v_lshlrev_b64 v[154:155], 12, v[152:153]
	v_lshl_add_u64 v[154:155], s[90:91], 0, v[154:155]
	v_lshlrev_b64 v[156:157], 1, v[144:145]
	v_lshl_add_u64 v[144:145], v[154:155], 0, v[156:157]
	v_cvt_pk_bf16_f32 v124, v124, v125
	v_cvt_pk_bf16_f32 v125, v126, v127
	v_cvt_pk_bf16_f32 v126, v120, v121
	v_cvt_pk_bf16_f32 v127, v122, v123
	global_store_dwordx4 v[144:145], v[124:127], off
	v_cvt_pk_bf16_f32 v112, v112, v113
	v_cvt_pk_bf16_f32 v113, v114, v115
	v_cvt_pk_bf16_f32 v114, v104, v105
	v_or_b32_e32 v104, 16, v152
	v_ashrrev_i32_e32 v105, 31, v104
	v_lshlrev_b64 v[104:105], 12, v[104:105]
	v_lshl_add_u64 v[104:105], s[90:91], 0, v[104:105]
	v_cvt_pk_bf16_f32 v115, v106, v107
	global_store_dwordx4 v[144:145], v[112:115], off offset:256
	s_mov_b32 s64, s61
	s_mov_b32 s63, s62
	v_lshl_add_u64 v[112:113], v[104:105], 0, v[156:157]
	v_cvt_pk_bf16_f32 v104, v116, v117
	v_cvt_pk_bf16_f32 v105, v118, v119
	v_cvt_pk_bf16_f32 v106, v108, v109
	v_cvt_pk_bf16_f32 v107, v110, v111
	global_store_dwordx4 v[112:113], v[104:107], off
	v_cvt_pk_bf16_f32 v96, v96, v97
	v_cvt_pk_bf16_f32 v97, v98, v99
	v_cvt_pk_bf16_f32 v98, v88, v89
	v_or_b32_e32 v88, 32, v152
	v_ashrrev_i32_e32 v89, 31, v88
	v_lshlrev_b64 v[88:89], 12, v[88:89]
	v_lshl_add_u64 v[88:89], s[90:91], 0, v[88:89]
	v_cvt_pk_bf16_f32 v99, v90, v91
	global_store_dwordx4 v[112:113], v[96:99], off offset:256
	s_mov_b64 s[34:35], s[8:9]
	s_mov_b64 s[26:27], s[6:7]
	v_lshl_add_u64 v[96:97], v[88:89], 0, v[156:157]
	v_cvt_pk_bf16_f32 v88, v100, v101
	v_cvt_pk_bf16_f32 v89, v102, v103
	v_cvt_pk_bf16_f32 v90, v92, v93
	v_cvt_pk_bf16_f32 v91, v94, v95
	global_store_dwordx4 v[96:97], v[88:91], off
	v_cvt_pk_bf16_f32 v80, v80, v81
	v_cvt_pk_bf16_f32 v81, v82, v83
	v_cvt_pk_bf16_f32 v82, v72, v73
	v_or_b32_e32 v72, 48, v152
	v_ashrrev_i32_e32 v73, 31, v72
	v_lshlrev_b64 v[72:73], 12, v[72:73]
	v_lshl_add_u64 v[72:73], s[90:91], 0, v[72:73]
	v_cvt_pk_bf16_f32 v83, v74, v75
	global_store_dwordx4 v[96:97], v[80:83], off offset:256
	s_nop 1
	v_lshl_add_u64 v[80:81], v[72:73], 0, v[156:157]
	v_cvt_pk_bf16_f32 v72, v84, v85
	v_cvt_pk_bf16_f32 v73, v86, v87
	v_cvt_pk_bf16_f32 v74, v76, v77
	v_cvt_pk_bf16_f32 v75, v78, v79
	global_store_dwordx4 v[80:81], v[72:75], off
	v_cvt_pk_bf16_f32 v68, v68, v69
	v_cvt_pk_bf16_f32 v69, v70, v71
	v_cvt_pk_bf16_f32 v70, v64, v65
	v_cvt_pk_bf16_f32 v71, v66, v67
	global_store_dwordx4 v[80:81], v[68:71], off offset:256
	v_cvt_pk_bf16_f32 v60, v60, v61
	v_cvt_pk_bf16_f32 v61, v62, v63
	v_cvt_pk_bf16_f32 v62, v56, v57
	v_add_co_u32_e32 v56, vcc, s57, v144
	v_lshl_add_u64 v[64:65], v[144:145], 0, s[16:17]
	s_nop 0
	v_addc_co_u32_e32 v57, vcc, 0, v145, vcc
	v_cvt_pk_bf16_f32 v63, v58, v59
	global_store_dwordx4 v[56:57], v[60:63], off
	v_cvt_pk_bf16_f32 v48, v48, v49
	v_cvt_pk_bf16_f32 v49, v50, v51
	v_cvt_pk_bf16_f32 v50, v40, v41
	v_cvt_pk_bf16_f32 v51, v42, v43
	global_store_dwordx4 v[64:65], v[48:51], off offset:256
	v_cvt_pk_bf16_f32 v40, v52, v53
	v_cvt_pk_bf16_f32 v41, v54, v55
	v_cvt_pk_bf16_f32 v42, v44, v45
	v_add_co_u32_e32 v44, vcc, s58, v144
	s_nop 0
	v_lshl_add_u64 v[48:49], v[144:145], 0, s[20:21]
	v_addc_co_u32_e32 v45, vcc, 0, v145, vcc
	v_cvt_pk_bf16_f32 v43, v46, v47
	global_store_dwordx4 v[44:45], v[40:43], off
	v_cvt_pk_bf16_f32 v32, v32, v33
	v_cvt_pk_bf16_f32 v33, v34, v35
	v_cvt_pk_bf16_f32 v34, v24, v25
	v_cvt_pk_bf16_f32 v35, v26, v27
	global_store_dwordx4 v[48:49], v[32:35], off offset:256
	v_cvt_pk_bf16_f32 v24, v36, v37
	v_cvt_pk_bf16_f32 v25, v38, v39
	v_cvt_pk_bf16_f32 v26, v28, v29
	v_add_co_u32_e32 v28, vcc, s59, v144
	s_nop 0
	v_lshl_add_u64 v[32:33], v[144:145], 0, s[22:23]
	v_addc_co_u32_e32 v29, vcc, 0, v145, vcc
	v_cvt_pk_bf16_f32 v27, v30, v31
	global_store_dwordx4 v[28:29], v[24:27], off
	v_cvt_pk_bf16_f32 v16, v16, v17
	v_cvt_pk_bf16_f32 v17, v18, v19
	v_cvt_pk_bf16_f32 v18, v8, v9
	v_cvt_pk_bf16_f32 v19, v10, v11
	global_store_dwordx4 v[32:33], v[16:19], off offset:256
	v_cvt_pk_bf16_f32 v8, v20, v21
	v_cvt_pk_bf16_f32 v9, v22, v23
	v_cvt_pk_bf16_f32 v10, v12, v13
	v_add_co_u32_e32 v12, vcc, s60, v144
	s_nop 0
	v_lshl_add_u64 v[16:17], v[144:145], 0, s[24:25]
	v_addc_co_u32_e32 v13, vcc, 0, v145, vcc
	s_and_b64 vcc, exec, s[4:5]
	v_cvt_pk_bf16_f32 v11, v14, v15
	global_store_dwordx4 v[12:13], v[8:11], off
	v_cvt_pk_bf16_f32 v4, v4, v5
	v_cvt_pk_bf16_f32 v5, v6, v7
	v_cvt_pk_bf16_f32 v6, v0, v1
	v_cvt_pk_bf16_f32 v7, v2, v3
	global_store_dwordx4 v[16:17], v[4:7], off offset:256
	s_cbranch_vccz .LBB0_541
	s_waitcnt vmcnt(0)
	s_cmpk_gt_u32 s0, 0xff
	s_cbranch_scc1 .LBB0_556
	s_barrier
